# all 7 one-stage GEMM loops: first K-iteration peeled with C=0 MFMAs, 128 v_mov accumulator zeroing removed; P12 epilogue-load prefetch
# speedup vs baseline: 1.0158x; 1.0081x over previous
.LBB0_566:
	s_ashr_i32 s9, s8, 31
	v_cmp_lt_i64_e32 vcc, s[10:11], v[144:145]
	s_lshl_b64 s[10:11], s[8:9], 19
	s_add_u32 s10, s40, s10
	s_addc_u32 s11, s41, s11
	s_and_b64 s[12:13], vcc, exec
	s_cselect_b32 s9, s11, s17
	s_cselect_b32 s75, s10, s16
	s_ashr_i32 s7, s6, 31
	s_lshl_b64 s[12:13], s[6:7], 19
	s_add_u32 s12, s48, s12
	s_addc_u32 s13, s49, s13
	s_and_b64 s[18:19], vcc, exec
	s_cselect_b32 s7, s13, s35
	s_cselect_b32 s76, s12, s34
	s_add_u32 s16, s16, 0x40080
	s_addc_u32 s17, s17, 0
	s_add_u32 s77, s34, 0x100
	s_addc_u32 s78, s35, 0
	s_mov_b32 s79, -2
	ds_read_b128 v[154:157], v151
	ds_read_b128 v[158:161], v151 offset:1024
	ds_read_b128 v[162:165], v151 offset:2048
	ds_read_b128 v[166:169], v151 offset:3072
	s_add_u32 s18, s16, 0xfffc0080
	s_addc_u32 s19, s17, -1
	s_cmp_eq_u32 s79, 12
	s_cselect_b32 s19, s9, s19
	s_cselect_b32 s18, s75, s18
	s_cselect_b32 s35, s7, s78
	s_cselect_b32 s34, s76, s77
	v_lshl_add_u64 v[172:173], s[16:17], 0, v[140:141]
	s_add_i32 m0, s53, 0xc000
	ds_read_b128 v[176:179], v152
	ds_read_b128 v[180:183], v152 offset:1024
	ds_read_b128 v[184:187], v152 offset:2048
	ds_read_b128 v[188:191], v152 offset:3072
	ds_read_b128 v[192:195], v152 offset:4096
	ds_read_b128 v[196:199], v152 offset:5120
	ds_read_b128 v[200:203], v152 offset:6144
	ds_read_b128 v[204:207], v152 offset:7168
	global_load_lds_dwordx4 v[172:173], off
	v_lshl_add_u64 v[172:173], s[16:17], 0, v[142:143]
	s_add_i32 m0, s53, 0xe000
	s_nop 0
	global_load_lds_dwordx4 v[172:173], off
	s_waitcnt lgkmcnt(8)
	s_barrier
	s_waitcnt lgkmcnt(0)
	s_setprio 1
	s_waitcnt lgkmcnt(0)
	v_mfma_f32_16x16x32_bf16 v[126:129], v[154:157], v[176:179], 0
	v_mfma_f32_16x16x32_bf16 v[122:125], v[162:165], v[176:179], 0
	v_mfma_f32_16x16x32_bf16 v[110:113], v[154:157], v[184:187], 0
	v_mfma_f32_16x16x32_bf16 v[106:109], v[162:165], v[184:187], 0
	v_mfma_f32_16x16x32_bf16 v[94:97], v[154:157], v[192:195], 0
	v_mfma_f32_16x16x32_bf16 v[90:93], v[162:165], v[192:195], 0
	v_mfma_f32_16x16x32_bf16 v[78:81], v[154:157], v[200:203], 0
	v_mfma_f32_16x16x32_bf16 v[74:77], v[162:165], v[200:203], 0
	v_mfma_f32_16x16x32_bf16 v[126:129], v[158:161], v[180:183], v[126:129]
	v_mfma_f32_16x16x32_bf16 v[122:125], v[166:169], v[180:183], v[122:125]
	v_mfma_f32_16x16x32_bf16 v[110:113], v[158:161], v[188:191], v[110:113]
	v_mfma_f32_16x16x32_bf16 v[106:109], v[166:169], v[188:191], v[106:109]
	v_mfma_f32_16x16x32_bf16 v[94:97], v[158:161], v[196:199], v[94:97]
	v_mfma_f32_16x16x32_bf16 v[90:93], v[166:169], v[196:199], v[90:93]
	v_mfma_f32_16x16x32_bf16 v[78:81], v[158:161], v[204:207], v[78:81]
	v_mfma_f32_16x16x32_bf16 v[74:77], v[166:169], v[204:207], v[74:77]
	s_setprio 0
	s_barrier
	s_add_i32 s20, s72, s52
	v_lshl_add_u64 v[172:173], s[34:35], 0, v[134:135]
	s_mov_b32 m0, s20
	ds_read_b128 v[208:211], v153
	ds_read_b128 v[212:215], v153 offset:1024
	ds_read_b128 v[216:219], v153 offset:2048
	ds_read_b128 v[220:223], v153 offset:3072
	global_load_lds_dwordx4 v[172:173], off
	v_lshl_add_u64 v[224:225], s[34:35], 0, v[130:131]
	s_add_i32 m0, s20, 0x2000
	s_nop 0
	global_load_lds_dwordx4 v[224:225], off
	s_barrier
	s_waitcnt lgkmcnt(0)
	s_setprio 1
	s_waitcnt lgkmcnt(0)
	v_mfma_f32_16x16x32_bf16 v[118:121], v[208:211], v[176:179], 0
	v_mfma_f32_16x16x32_bf16 v[114:117], v[216:219], v[176:179], 0
	v_mfma_f32_16x16x32_bf16 v[102:105], v[208:211], v[184:187], 0
	v_mfma_f32_16x16x32_bf16 v[98:101], v[216:219], v[184:187], 0
	v_mfma_f32_16x16x32_bf16 v[86:89], v[208:211], v[192:195], 0
	v_mfma_f32_16x16x32_bf16 v[82:85], v[216:219], v[192:195], 0
	v_mfma_f32_16x16x32_bf16 v[70:73], v[208:211], v[200:203], 0
	v_mfma_f32_16x16x32_bf16 v[66:69], v[216:219], v[200:203], 0
	v_mfma_f32_16x16x32_bf16 v[118:121], v[212:215], v[180:183], v[118:121]
	v_mfma_f32_16x16x32_bf16 v[114:117], v[220:223], v[180:183], v[114:117]
	v_mfma_f32_16x16x32_bf16 v[102:105], v[212:215], v[188:191], v[102:105]
	v_mfma_f32_16x16x32_bf16 v[98:101], v[220:223], v[188:191], v[98:101]
	v_mfma_f32_16x16x32_bf16 v[86:89], v[212:215], v[196:199], v[86:89]
	v_mfma_f32_16x16x32_bf16 v[82:85], v[220:223], v[196:199], v[82:85]
	v_mfma_f32_16x16x32_bf16 v[70:73], v[212:215], v[204:207], v[70:73]
	v_mfma_f32_16x16x32_bf16 v[66:69], v[220:223], v[204:207], v[66:69]
	s_setprio 0
	s_mov_b32 m0, s53
	v_lshl_add_u64 v[226:227], s[18:19], 0, v[136:137]
	s_barrier
	ds_read_b128 v[176:179], v152 offset:16384
	ds_read_b128 v[180:183], v152 offset:17408
	ds_read_b128 v[184:187], v152 offset:18432
	ds_read_b128 v[188:191], v152 offset:19456
	ds_read_b128 v[192:195], v152 offset:20480
	ds_read_b128 v[196:199], v152 offset:21504
	ds_read_b128 v[200:203], v152 offset:22528
	ds_read_b128 v[204:207], v152 offset:23552
	global_load_lds_dwordx4 v[226:227], off
	v_lshl_add_u64 v[228:229], s[18:19], 0, v[132:133]
	s_mov_b32 m0, s54
	s_nop 0
	global_load_lds_dwordx4 v[228:229], off
	s_barrier
	s_waitcnt lgkmcnt(0)
	s_setprio 1
	s_waitcnt lgkmcnt(0)
	v_mfma_f32_16x16x32_bf16 v[62:65], v[154:157], v[176:179], 0
	v_mfma_f32_16x16x32_bf16 v[58:61], v[162:165], v[176:179], 0
	v_mfma_f32_16x16x32_bf16 v[46:49], v[154:157], v[184:187], 0
	v_mfma_f32_16x16x32_bf16 v[42:45], v[162:165], v[184:187], 0
	v_mfma_f32_16x16x32_bf16 v[30:33], v[154:157], v[192:195], 0
	v_mfma_f32_16x16x32_bf16 v[26:29], v[162:165], v[192:195], 0
	v_mfma_f32_16x16x32_bf16 v[14:17], v[154:157], v[200:203], 0
	v_mfma_f32_16x16x32_bf16 v[10:13], v[162:165], v[200:203], 0
	v_mfma_f32_16x16x32_bf16 v[62:65], v[158:161], v[180:183], v[62:65]
	v_mfma_f32_16x16x32_bf16 v[58:61], v[166:169], v[180:183], v[58:61]
	v_mfma_f32_16x16x32_bf16 v[46:49], v[158:161], v[188:191], v[46:49]
	v_mfma_f32_16x16x32_bf16 v[42:45], v[166:169], v[188:191], v[42:45]
	v_mfma_f32_16x16x32_bf16 v[30:33], v[158:161], v[196:199], v[30:33]
	v_mfma_f32_16x16x32_bf16 v[26:29], v[166:169], v[196:199], v[26:29]
	v_mfma_f32_16x16x32_bf16 v[14:17], v[158:161], v[204:207], v[14:17]
	v_mfma_f32_16x16x32_bf16 v[10:13], v[166:169], v[204:207], v[10:13]
	s_setprio 0
	s_barrier
	s_add_u32 s20, s34, 0x40000
	s_addc_u32 s21, s35, 0
	s_add_i32 s60, s73, s52
	v_lshl_add_u64 v[154:155], s[20:21], 0, v[134:135]
	s_mov_b32 m0, s60
	s_nop 0
	global_load_lds_dwordx4 v[154:155], off
	v_lshl_add_u64 v[154:155], s[20:21], 0, v[130:131]
	s_add_i32 m0, s60, 0x2000
	s_nop 0
	global_load_lds_dwordx4 v[154:155], off
	s_waitcnt vmcnt(6)
	s_barrier
	s_setprio 1
	v_mfma_f32_16x16x32_bf16 v[54:57], v[208:211], v[176:179], 0
	v_mfma_f32_16x16x32_bf16 v[50:53], v[216:219], v[176:179], 0
	v_mfma_f32_16x16x32_bf16 v[38:41], v[208:211], v[184:187], 0
	v_mfma_f32_16x16x32_bf16 v[34:37], v[216:219], v[184:187], 0
	v_mfma_f32_16x16x32_bf16 v[22:25], v[208:211], v[192:195], 0
	v_mfma_f32_16x16x32_bf16 v[18:21], v[216:219], v[192:195], 0
	v_mfma_f32_16x16x32_bf16 v[6:9], v[208:211], v[200:203], 0
	v_mfma_f32_16x16x32_bf16 v[2:5], v[216:219], v[200:203], 0
	v_mfma_f32_16x16x32_bf16 v[54:57], v[212:215], v[180:183], v[54:57]
	v_mfma_f32_16x16x32_bf16 v[50:53], v[220:223], v[180:183], v[50:53]
	v_mfma_f32_16x16x32_bf16 v[38:41], v[212:215], v[188:191], v[38:41]
	v_mfma_f32_16x16x32_bf16 v[34:37], v[220:223], v[188:191], v[34:37]
	v_mfma_f32_16x16x32_bf16 v[22:25], v[212:215], v[196:199], v[22:25]
	v_mfma_f32_16x16x32_bf16 v[18:21], v[220:223], v[196:199], v[18:21]
	v_mfma_f32_16x16x32_bf16 v[6:9], v[212:215], v[204:207], v[6:9]
	v_mfma_f32_16x16x32_bf16 v[2:5], v[220:223], v[204:207], v[2:5]
	s_setprio 0
	s_add_i32 s20, 0, 0x18000
	v_add_u32_e32 v166, s20, v150
	s_barrier
	ds_read_b128 v[154:157], v166
	ds_read_b128 v[158:161], v166 offset:1024
	ds_read_b128 v[162:165], v166 offset:2048
	ds_read_b128 v[166:169], v166 offset:3072
	s_add_u32 s18, s18, 0x40000
	s_addc_u32 s19, s19, 0
	s_mov_b32 m0, s55
	v_lshl_add_u64 v[208:209], s[18:19], 0, v[136:137]
	ds_read_b128 v[176:179], v152 offset:32768
	ds_read_b128 v[180:183], v152 offset:33792
	ds_read_b128 v[184:187], v152 offset:34816
	ds_read_b128 v[188:191], v152 offset:35840
	ds_read_b128 v[192:195], v152 offset:36864
	ds_read_b128 v[196:199], v152 offset:37888
	ds_read_b128 v[200:203], v152 offset:38912
	ds_read_b128 v[204:207], v152 offset:39936
	global_load_lds_dwordx4 v[208:209], off
	v_lshl_add_u64 v[208:209], s[18:19], 0, v[132:133]
	s_mov_b32 m0, s56
	s_nop 0
	global_load_lds_dwordx4 v[208:209], off
	s_waitcnt lgkmcnt(8)
	s_barrier
	s_waitcnt lgkmcnt(0)
	s_setprio 1
	s_waitcnt lgkmcnt(0)
	v_mfma_f32_16x16x32_bf16 v[126:129], v[154:157], v[176:179], v[126:129]
	v_mfma_f32_16x16x32_bf16 v[122:125], v[162:165], v[176:179], v[122:125]
	v_mfma_f32_16x16x32_bf16 v[110:113], v[154:157], v[184:187], v[110:113]
	v_mfma_f32_16x16x32_bf16 v[106:109], v[162:165], v[184:187], v[106:109]
	v_mfma_f32_16x16x32_bf16 v[94:97], v[154:157], v[192:195], v[94:97]
	v_mfma_f32_16x16x32_bf16 v[90:93], v[162:165], v[192:195], v[90:93]
	v_mfma_f32_16x16x32_bf16 v[78:81], v[154:157], v[200:203], v[78:81]
	v_mfma_f32_16x16x32_bf16 v[74:77], v[162:165], v[200:203], v[74:77]
	v_mfma_f32_16x16x32_bf16 v[126:129], v[158:161], v[180:183], v[126:129]
	v_mfma_f32_16x16x32_bf16 v[122:125], v[166:169], v[180:183], v[122:125]
	v_mfma_f32_16x16x32_bf16 v[110:113], v[158:161], v[188:191], v[110:113]
	v_mfma_f32_16x16x32_bf16 v[106:109], v[166:169], v[188:191], v[106:109]
	v_mfma_f32_16x16x32_bf16 v[94:97], v[158:161], v[196:199], v[94:97]
	v_mfma_f32_16x16x32_bf16 v[90:93], v[166:169], v[196:199], v[90:93]
	v_mfma_f32_16x16x32_bf16 v[78:81], v[158:161], v[204:207], v[78:81]
	v_mfma_f32_16x16x32_bf16 v[74:77], v[166:169], v[204:207], v[74:77]
	s_setprio 0
	s_barrier
	s_add_i32 s21, 0, 0x1c000
	s_add_i32 s18, s20, s52
	v_add_u32_e32 v171, s21, v150
	v_lshl_add_u64 v[172:173], v[172:173], 0, s[4:5]
	s_mov_b32 m0, s18
	ds_read_b128 v[208:211], v171
	ds_read_b128 v[212:215], v171 offset:1024
	ds_read_b128 v[216:219], v171 offset:2048
	ds_read_b128 v[220:223], v171 offset:3072
	global_load_lds_dwordx4 v[172:173], off
	v_lshl_add_u64 v[172:173], v[224:225], 0, s[4:5]
	s_add_i32 m0, s18, 0x2000
	s_nop 0
	global_load_lds_dwordx4 v[172:173], off
	s_barrier
	s_waitcnt lgkmcnt(0)
	s_setprio 1
	s_waitcnt lgkmcnt(0)
	v_mfma_f32_16x16x32_bf16 v[118:121], v[208:211], v[176:179], v[118:121]
	v_mfma_f32_16x16x32_bf16 v[114:117], v[216:219], v[176:179], v[114:117]
	v_mfma_f32_16x16x32_bf16 v[102:105], v[208:211], v[184:187], v[102:105]
	v_mfma_f32_16x16x32_bf16 v[98:101], v[216:219], v[184:187], v[98:101]
	v_mfma_f32_16x16x32_bf16 v[86:89], v[208:211], v[192:195], v[86:89]
	v_mfma_f32_16x16x32_bf16 v[82:85], v[216:219], v[192:195], v[82:85]
	v_mfma_f32_16x16x32_bf16 v[70:73], v[208:211], v[200:203], v[70:73]
	v_mfma_f32_16x16x32_bf16 v[66:69], v[216:219], v[200:203], v[66:69]
	v_mfma_f32_16x16x32_bf16 v[118:121], v[212:215], v[180:183], v[118:121]
	v_mfma_f32_16x16x32_bf16 v[114:117], v[220:223], v[180:183], v[114:117]
	v_mfma_f32_16x16x32_bf16 v[102:105], v[212:215], v[188:191], v[102:105]
	v_mfma_f32_16x16x32_bf16 v[98:101], v[220:223], v[188:191], v[98:101]
	v_mfma_f32_16x16x32_bf16 v[86:89], v[212:215], v[196:199], v[86:89]
	v_mfma_f32_16x16x32_bf16 v[82:85], v[220:223], v[196:199], v[82:85]
	v_mfma_f32_16x16x32_bf16 v[70:73], v[212:215], v[204:207], v[70:73]
	v_mfma_f32_16x16x32_bf16 v[66:69], v[220:223], v[204:207], v[66:69]
	s_setprio 0
	s_mov_b32 m0, s68
	v_lshl_add_u64 v[172:173], v[226:227], 0, s[4:5]
	s_barrier
	ds_read_b128 v[176:179], v152 offset:49152
	ds_read_b128 v[180:183], v152 offset:50176
	ds_read_b128 v[184:187], v152 offset:51200
	ds_read_b128 v[188:191], v152 offset:52224
	ds_read_b128 v[192:195], v152 offset:53248
	ds_read_b128 v[196:199], v152 offset:54272
	ds_read_b128 v[200:203], v152 offset:55296
	ds_read_b128 v[204:207], v152 offset:56320
	global_load_lds_dwordx4 v[172:173], off
	v_lshl_add_u64 v[172:173], v[228:229], 0, s[4:5]
	s_mov_b32 m0, s69
	s_nop 0
	global_load_lds_dwordx4 v[172:173], off
	s_barrier
	s_waitcnt lgkmcnt(0)
	s_setprio 1
	s_waitcnt lgkmcnt(0)
	v_mfma_f32_16x16x32_bf16 v[62:65], v[154:157], v[176:179], v[62:65]
	v_mfma_f32_16x16x32_bf16 v[58:61], v[162:165], v[176:179], v[58:61]
	v_mfma_f32_16x16x32_bf16 v[46:49], v[154:157], v[184:187], v[46:49]
	v_mfma_f32_16x16x32_bf16 v[42:45], v[162:165], v[184:187], v[42:45]
	v_mfma_f32_16x16x32_bf16 v[30:33], v[154:157], v[192:195], v[30:33]
	v_mfma_f32_16x16x32_bf16 v[26:29], v[162:165], v[192:195], v[26:29]
	v_mfma_f32_16x16x32_bf16 v[14:17], v[154:157], v[200:203], v[14:17]
	v_mfma_f32_16x16x32_bf16 v[10:13], v[162:165], v[200:203], v[10:13]
	v_mfma_f32_16x16x32_bf16 v[62:65], v[158:161], v[180:183], v[62:65]
	v_mfma_f32_16x16x32_bf16 v[58:61], v[166:169], v[180:183], v[58:61]
	v_mfma_f32_16x16x32_bf16 v[46:49], v[158:161], v[188:191], v[46:49]
	v_mfma_f32_16x16x32_bf16 v[42:45], v[166:169], v[188:191], v[42:45]
	v_mfma_f32_16x16x32_bf16 v[30:33], v[158:161], v[196:199], v[30:33]
	v_mfma_f32_16x16x32_bf16 v[26:29], v[166:169], v[196:199], v[26:29]
	v_mfma_f32_16x16x32_bf16 v[14:17], v[158:161], v[204:207], v[14:17]
	v_mfma_f32_16x16x32_bf16 v[10:13], v[166:169], v[204:207], v[10:13]
	s_setprio 0
	s_barrier
	s_add_u32 s18, s34, 0x40080
	s_addc_u32 s19, s35, 0
	s_add_i32 s20, s21, s52
	v_lshl_add_u64 v[154:155], s[18:19], 0, v[134:135]
	s_mov_b32 m0, s20
	s_nop 0
	global_load_lds_dwordx4 v[154:155], off
	v_lshl_add_u64 v[154:155], s[18:19], 0, v[130:131]
	s_add_i32 m0, s20, 0x2000
	s_nop 0
	global_load_lds_dwordx4 v[154:155], off
	s_waitcnt vmcnt(6)
	s_barrier
	s_setprio 1
	v_mfma_f32_16x16x32_bf16 v[54:57], v[208:211], v[176:179], v[54:57]
	v_mfma_f32_16x16x32_bf16 v[50:53], v[216:219], v[176:179], v[50:53]
	v_mfma_f32_16x16x32_bf16 v[38:41], v[208:211], v[184:187], v[38:41]
	v_mfma_f32_16x16x32_bf16 v[34:37], v[216:219], v[184:187], v[34:37]
	v_mfma_f32_16x16x32_bf16 v[22:25], v[208:211], v[192:195], v[22:25]
	v_mfma_f32_16x16x32_bf16 v[18:21], v[216:219], v[192:195], v[18:21]
	v_mfma_f32_16x16x32_bf16 v[6:9], v[208:211], v[200:203], v[6:9]
	v_mfma_f32_16x16x32_bf16 v[2:5], v[216:219], v[200:203], v[2:5]
	v_mfma_f32_16x16x32_bf16 v[54:57], v[212:215], v[180:183], v[54:57]
	v_mfma_f32_16x16x32_bf16 v[50:53], v[220:223], v[180:183], v[50:53]
	v_mfma_f32_16x16x32_bf16 v[38:41], v[212:215], v[188:191], v[38:41]
	v_mfma_f32_16x16x32_bf16 v[34:37], v[220:223], v[188:191], v[34:37]
	v_mfma_f32_16x16x32_bf16 v[22:25], v[212:215], v[196:199], v[22:25]
	v_mfma_f32_16x16x32_bf16 v[18:21], v[220:223], v[196:199], v[18:21]
	v_mfma_f32_16x16x32_bf16 v[6:9], v[212:215], v[204:207], v[6:9]
	v_mfma_f32_16x16x32_bf16 v[2:5], v[220:223], v[204:207], v[2:5]
	s_setprio 0
	s_add_i32 s79, s79, 2
	s_add_u32 s16, s16, 0x100
	s_addc_u32 s17, s17, 0
	s_add_u32 s77, s77, 0x100
	s_addc_u32 s78, s78, 0
	s_cmp_gt_u32 s79, 13
	s_barrier

.LBB0_821:
	s_add_u32 s0, s10, 0xb0080
	s_addc_u32 s1, s11, 0
	s_add_u32 s10, s8, 0x100
	s_addc_u32 s11, s9, 0
	s_mov_b32 s49, -2
	s_waitcnt lgkmcnt(0)
	ds_read_b128 v[130:133], v241
	ds_read_b128 v[134:137], v241 offset:1024
	ds_read_b128 v[138:141], v241 offset:2048
	ds_read_b128 v[142:145], v241 offset:3072
	s_add_u32 s6, s0, 0xfff50080
	s_addc_u32 s7, s1, -1
	s_cmp_eq_u32 s49, 40
	s_cselect_b32 s9, s39, s7
	s_cselect_b32 s8, s38, s6
	s_cselect_b32 s7, s41, s11
	s_cselect_b32 s6, s40, s10
	v_lshl_add_u64 v[202:203], s[0:1], 0, v[186:187]
	s_add_i32 m0, s57, 0xc000
	ds_read_b128 v[146:149], v242
	ds_read_b128 v[150:153], v242 offset:1024
	ds_read_b128 v[154:157], v242 offset:2048
	ds_read_b128 v[158:161], v242 offset:3072
	ds_read_b128 v[162:165], v242 offset:4096
	ds_read_b128 v[166:169], v242 offset:5120
	ds_read_b128 v[194:197], v242 offset:6144
	ds_read_b128 v[198:201], v242 offset:7168
	global_load_lds_dwordx4 v[202:203], off
	v_lshl_add_u64 v[202:203], s[0:1], 0, v[188:189]
	s_add_i32 m0, s57, 0xe000
	s_nop 0
	global_load_lds_dwordx4 v[202:203], off
	s_waitcnt lgkmcnt(8)
	s_barrier
	s_waitcnt lgkmcnt(0)
	s_setprio 1
	s_waitcnt lgkmcnt(0)
	v_mfma_f32_16x16x32_bf16 v[126:129], v[130:133], v[146:149], 0
	v_mfma_f32_16x16x32_bf16 v[122:125], v[138:141], v[146:149], 0
	v_mfma_f32_16x16x32_bf16 v[110:113], v[130:133], v[154:157], 0
	v_mfma_f32_16x16x32_bf16 v[106:109], v[138:141], v[154:157], 0
	v_mfma_f32_16x16x32_bf16 v[94:97], v[130:133], v[162:165], 0
	v_mfma_f32_16x16x32_bf16 v[90:93], v[138:141], v[162:165], 0
	v_mfma_f32_16x16x32_bf16 v[78:81], v[130:133], v[194:197], 0
	v_mfma_f32_16x16x32_bf16 v[74:77], v[138:141], v[194:197], 0
	v_mfma_f32_16x16x32_bf16 v[126:129], v[134:137], v[150:153], v[126:129]
	v_mfma_f32_16x16x32_bf16 v[122:125], v[142:145], v[150:153], v[122:125]
	v_mfma_f32_16x16x32_bf16 v[110:113], v[134:137], v[158:161], v[110:113]
	v_mfma_f32_16x16x32_bf16 v[106:109], v[142:145], v[158:161], v[106:109]
	v_mfma_f32_16x16x32_bf16 v[94:97], v[134:137], v[166:169], v[94:97]
	v_mfma_f32_16x16x32_bf16 v[90:93], v[142:145], v[166:169], v[90:93]
	v_mfma_f32_16x16x32_bf16 v[78:81], v[134:137], v[198:201], v[78:81]
	v_mfma_f32_16x16x32_bf16 v[74:77], v[142:145], v[198:201], v[74:77]
	s_setprio 0
	s_barrier
	s_add_i32 s20, s77, s56
	v_lshl_add_u64 v[218:219], s[6:7], 0, v[176:177]
	s_mov_b32 m0, s20
	ds_read_b128 v[202:205], v243
	ds_read_b128 v[206:209], v243 offset:1024
	ds_read_b128 v[210:213], v243 offset:2048
	ds_read_b128 v[214:217], v243 offset:3072
	global_load_lds_dwordx4 v[218:219], off
	v_lshl_add_u64 v[220:221], s[6:7], 0, v[180:181]
	s_add_i32 m0, s20, 0x2000
	s_nop 0
	global_load_lds_dwordx4 v[220:221], off
	s_barrier
	s_waitcnt lgkmcnt(0)
	s_setprio 1
	s_waitcnt lgkmcnt(0)
	v_mfma_f32_16x16x32_bf16 v[118:121], v[202:205], v[146:149], 0
	v_mfma_f32_16x16x32_bf16 v[114:117], v[210:213], v[146:149], 0
	v_mfma_f32_16x16x32_bf16 v[102:105], v[202:205], v[154:157], 0
	v_mfma_f32_16x16x32_bf16 v[98:101], v[210:213], v[154:157], 0
	v_mfma_f32_16x16x32_bf16 v[86:89], v[202:205], v[162:165], 0
	v_mfma_f32_16x16x32_bf16 v[82:85], v[210:213], v[162:165], 0
	v_mfma_f32_16x16x32_bf16 v[70:73], v[202:205], v[194:197], 0
	v_mfma_f32_16x16x32_bf16 v[66:69], v[210:213], v[194:197], 0
	v_mfma_f32_16x16x32_bf16 v[118:121], v[206:209], v[150:153], v[118:121]
	v_mfma_f32_16x16x32_bf16 v[114:117], v[214:217], v[150:153], v[114:117]
	v_mfma_f32_16x16x32_bf16 v[102:105], v[206:209], v[158:161], v[102:105]
	v_mfma_f32_16x16x32_bf16 v[98:101], v[214:217], v[158:161], v[98:101]
	v_mfma_f32_16x16x32_bf16 v[86:89], v[206:209], v[166:169], v[86:89]
	v_mfma_f32_16x16x32_bf16 v[82:85], v[214:217], v[166:169], v[82:85]
	v_mfma_f32_16x16x32_bf16 v[70:73], v[206:209], v[198:201], v[70:73]
	v_mfma_f32_16x16x32_bf16 v[66:69], v[214:217], v[198:201], v[66:69]
	s_setprio 0
	s_mov_b32 m0, s57
	v_lshl_add_u64 v[222:223], s[8:9], 0, v[172:173]
	s_barrier
	ds_read_b128 v[146:149], v242 offset:16384
	ds_read_b128 v[150:153], v242 offset:17408
	ds_read_b128 v[154:157], v242 offset:18432
	ds_read_b128 v[158:161], v242 offset:19456
	ds_read_b128 v[162:165], v242 offset:20480
	ds_read_b128 v[166:169], v242 offset:21504
	ds_read_b128 v[194:197], v242 offset:22528
	ds_read_b128 v[198:201], v242 offset:23552
	global_load_lds_dwordx4 v[222:223], off
	v_lshl_add_u64 v[224:225], s[8:9], 0, v[178:179]
	s_mov_b32 m0, s68
	s_nop 0
	global_load_lds_dwordx4 v[224:225], off
	s_barrier
	s_waitcnt lgkmcnt(0)
	s_setprio 1
	s_waitcnt lgkmcnt(0)
	v_mfma_f32_16x16x32_bf16 v[62:65], v[130:133], v[146:149], 0
	v_mfma_f32_16x16x32_bf16 v[58:61], v[138:141], v[146:149], 0
	v_mfma_f32_16x16x32_bf16 v[46:49], v[130:133], v[154:157], 0
	v_mfma_f32_16x16x32_bf16 v[42:45], v[138:141], v[154:157], 0
	v_mfma_f32_16x16x32_bf16 v[30:33], v[130:133], v[162:165], 0
	v_mfma_f32_16x16x32_bf16 v[26:29], v[138:141], v[162:165], 0
	v_mfma_f32_16x16x32_bf16 v[14:17], v[130:133], v[194:197], 0
	v_mfma_f32_16x16x32_bf16 v[10:13], v[138:141], v[194:197], 0
	v_mfma_f32_16x16x32_bf16 v[62:65], v[134:137], v[150:153], v[62:65]
	v_mfma_f32_16x16x32_bf16 v[58:61], v[142:145], v[150:153], v[58:61]
	v_mfma_f32_16x16x32_bf16 v[46:49], v[134:137], v[158:161], v[46:49]
	v_mfma_f32_16x16x32_bf16 v[42:45], v[142:145], v[158:161], v[42:45]
	v_mfma_f32_16x16x32_bf16 v[30:33], v[134:137], v[166:169], v[30:33]
	v_mfma_f32_16x16x32_bf16 v[26:29], v[142:145], v[166:169], v[26:29]
	v_mfma_f32_16x16x32_bf16 v[14:17], v[134:137], v[198:201], v[14:17]
	v_mfma_f32_16x16x32_bf16 v[10:13], v[142:145], v[198:201], v[10:13]
	s_setprio 0
	s_barrier
	s_add_u32 s20, s6, 0xb0000
	s_addc_u32 s21, s7, 0
	s_add_i32 s50, s78, s56
	v_lshl_add_u64 v[130:131], s[20:21], 0, v[176:177]
	s_mov_b32 m0, s50
	s_nop 0
	global_load_lds_dwordx4 v[130:131], off
	v_lshl_add_u64 v[130:131], s[20:21], 0, v[180:181]
	s_add_i32 m0, s50, 0x2000
	s_nop 0
	global_load_lds_dwordx4 v[130:131], off
	s_waitcnt vmcnt(6)
	s_barrier
	s_setprio 1
	v_mfma_f32_16x16x32_bf16 v[54:57], v[202:205], v[146:149], 0
	v_mfma_f32_16x16x32_bf16 v[50:53], v[210:213], v[146:149], 0
	v_mfma_f32_16x16x32_bf16 v[38:41], v[202:205], v[154:157], 0
	v_mfma_f32_16x16x32_bf16 v[34:37], v[210:213], v[154:157], 0
	v_mfma_f32_16x16x32_bf16 v[22:25], v[202:205], v[162:165], 0
	v_mfma_f32_16x16x32_bf16 v[18:21], v[210:213], v[162:165], 0
	v_mfma_f32_16x16x32_bf16 v[6:9], v[202:205], v[194:197], 0
	v_mfma_f32_16x16x32_bf16 v[2:5], v[210:213], v[194:197], 0
	v_mfma_f32_16x16x32_bf16 v[54:57], v[206:209], v[150:153], v[54:57]
	v_mfma_f32_16x16x32_bf16 v[50:53], v[214:217], v[150:153], v[50:53]
	v_mfma_f32_16x16x32_bf16 v[38:41], v[206:209], v[158:161], v[38:41]
	v_mfma_f32_16x16x32_bf16 v[34:37], v[214:217], v[158:161], v[34:37]
	v_mfma_f32_16x16x32_bf16 v[22:25], v[206:209], v[166:169], v[22:25]
	v_mfma_f32_16x16x32_bf16 v[18:21], v[214:217], v[166:169], v[18:21]
	v_mfma_f32_16x16x32_bf16 v[6:9], v[206:209], v[198:201], v[6:9]
	v_mfma_f32_16x16x32_bf16 v[2:5], v[214:217], v[198:201], v[2:5]
	s_setprio 0
	s_add_i32 s20, 0, 0x18000
	v_add_u32_e32 v142, s20, v240
	s_barrier
	ds_read_b128 v[130:133], v142
	ds_read_b128 v[134:137], v142 offset:1024
	ds_read_b128 v[138:141], v142 offset:2048
	ds_read_b128 v[142:145], v142 offset:3072
	s_add_u32 s8, s8, 0xb0000
	s_addc_u32 s9, s9, 0
	s_mov_b32 m0, s69
	v_lshl_add_u64 v[202:203], s[8:9], 0, v[172:173]
	ds_read_b128 v[146:149], v242 offset:32768
	ds_read_b128 v[150:153], v242 offset:33792
	ds_read_b128 v[154:157], v242 offset:34816
	ds_read_b128 v[158:161], v242 offset:35840
	ds_read_b128 v[162:165], v242 offset:36864
	ds_read_b128 v[166:169], v242 offset:37888
	ds_read_b128 v[194:197], v242 offset:38912
	ds_read_b128 v[198:201], v242 offset:39936
	global_load_lds_dwordx4 v[202:203], off
	v_lshl_add_u64 v[202:203], s[8:9], 0, v[178:179]
	s_mov_b32 m0, s70
	s_nop 0
	global_load_lds_dwordx4 v[202:203], off
	s_waitcnt lgkmcnt(8)
	s_barrier
	s_waitcnt lgkmcnt(0)
	s_setprio 1
	s_waitcnt lgkmcnt(0)
	v_mfma_f32_16x16x32_bf16 v[126:129], v[130:133], v[146:149], v[126:129]
	v_mfma_f32_16x16x32_bf16 v[122:125], v[138:141], v[146:149], v[122:125]
	v_mfma_f32_16x16x32_bf16 v[110:113], v[130:133], v[154:157], v[110:113]
	v_mfma_f32_16x16x32_bf16 v[106:109], v[138:141], v[154:157], v[106:109]
	v_mfma_f32_16x16x32_bf16 v[94:97], v[130:133], v[162:165], v[94:97]
	v_mfma_f32_16x16x32_bf16 v[90:93], v[138:141], v[162:165], v[90:93]
	v_mfma_f32_16x16x32_bf16 v[78:81], v[130:133], v[194:197], v[78:81]
	v_mfma_f32_16x16x32_bf16 v[74:77], v[138:141], v[194:197], v[74:77]
	v_mfma_f32_16x16x32_bf16 v[126:129], v[134:137], v[150:153], v[126:129]
	v_mfma_f32_16x16x32_bf16 v[122:125], v[142:145], v[150:153], v[122:125]
	v_mfma_f32_16x16x32_bf16 v[110:113], v[134:137], v[158:161], v[110:113]
	v_mfma_f32_16x16x32_bf16 v[106:109], v[142:145], v[158:161], v[106:109]
	v_mfma_f32_16x16x32_bf16 v[94:97], v[134:137], v[166:169], v[94:97]
	v_mfma_f32_16x16x32_bf16 v[90:93], v[142:145], v[166:169], v[90:93]
	v_mfma_f32_16x16x32_bf16 v[78:81], v[134:137], v[198:201], v[78:81]
	v_mfma_f32_16x16x32_bf16 v[74:77], v[142:145], v[198:201], v[74:77]
	s_setprio 0
	s_barrier
	s_add_i32 s8, 0, 0x1c000
	s_add_i32 s9, s20, s56
	v_add_u32_e32 v184, s8, v240
	v_lshl_add_u64 v[218:219], v[218:219], 0, s[16:17]
	s_mov_b32 m0, s9
	ds_read_b128 v[202:205], v184
	ds_read_b128 v[206:209], v184 offset:1024
	ds_read_b128 v[210:213], v184 offset:2048
	ds_read_b128 v[214:217], v184 offset:3072
	global_load_lds_dwordx4 v[218:219], off
	v_lshl_add_u64 v[218:219], v[220:221], 0, s[16:17]
	s_add_i32 m0, s9, 0x2000
	s_nop 0
	global_load_lds_dwordx4 v[218:219], off
	s_barrier
	s_waitcnt lgkmcnt(0)
	s_setprio 1
	s_waitcnt lgkmcnt(0)
	v_mfma_f32_16x16x32_bf16 v[118:121], v[202:205], v[146:149], v[118:121]
	v_mfma_f32_16x16x32_bf16 v[114:117], v[210:213], v[146:149], v[114:117]
	v_mfma_f32_16x16x32_bf16 v[102:105], v[202:205], v[154:157], v[102:105]
	v_mfma_f32_16x16x32_bf16 v[98:101], v[210:213], v[154:157], v[98:101]
	v_mfma_f32_16x16x32_bf16 v[86:89], v[202:205], v[162:165], v[86:89]
	v_mfma_f32_16x16x32_bf16 v[82:85], v[210:213], v[162:165], v[82:85]
	v_mfma_f32_16x16x32_bf16 v[70:73], v[202:205], v[194:197], v[70:73]
	v_mfma_f32_16x16x32_bf16 v[66:69], v[210:213], v[194:197], v[66:69]
	v_mfma_f32_16x16x32_bf16 v[118:121], v[206:209], v[150:153], v[118:121]
	v_mfma_f32_16x16x32_bf16 v[114:117], v[214:217], v[150:153], v[114:117]
	v_mfma_f32_16x16x32_bf16 v[102:105], v[206:209], v[158:161], v[102:105]
	v_mfma_f32_16x16x32_bf16 v[98:101], v[214:217], v[158:161], v[98:101]
	v_mfma_f32_16x16x32_bf16 v[86:89], v[206:209], v[166:169], v[86:89]
	v_mfma_f32_16x16x32_bf16 v[82:85], v[214:217], v[166:169], v[82:85]
	v_mfma_f32_16x16x32_bf16 v[70:73], v[206:209], v[198:201], v[70:73]
	v_mfma_f32_16x16x32_bf16 v[66:69], v[214:217], v[198:201], v[66:69]
	s_setprio 0
	s_mov_b32 m0, s74
	v_lshl_add_u64 v[218:219], v[222:223], 0, s[16:17]
	s_barrier
	ds_read_b128 v[146:149], v242 offset:49152
	ds_read_b128 v[150:153], v242 offset:50176
	ds_read_b128 v[154:157], v242 offset:51200
	ds_read_b128 v[158:161], v242 offset:52224
	ds_read_b128 v[162:165], v242 offset:53248
	ds_read_b128 v[166:169], v242 offset:54272
	ds_read_b128 v[194:197], v242 offset:55296
	ds_read_b128 v[198:201], v242 offset:56320
	global_load_lds_dwordx4 v[218:219], off
	v_lshl_add_u64 v[218:219], v[224:225], 0, s[16:17]
	s_mov_b32 m0, s75
	s_nop 0
	global_load_lds_dwordx4 v[218:219], off
	s_barrier
	s_waitcnt lgkmcnt(0)
	s_setprio 1
	s_waitcnt lgkmcnt(0)
	v_mfma_f32_16x16x32_bf16 v[62:65], v[130:133], v[146:149], v[62:65]
	v_mfma_f32_16x16x32_bf16 v[58:61], v[138:141], v[146:149], v[58:61]
	v_mfma_f32_16x16x32_bf16 v[46:49], v[130:133], v[154:157], v[46:49]
	v_mfma_f32_16x16x32_bf16 v[42:45], v[138:141], v[154:157], v[42:45]
	v_mfma_f32_16x16x32_bf16 v[30:33], v[130:133], v[162:165], v[30:33]
	v_mfma_f32_16x16x32_bf16 v[26:29], v[138:141], v[162:165], v[26:29]
	v_mfma_f32_16x16x32_bf16 v[14:17], v[130:133], v[194:197], v[14:17]
	v_mfma_f32_16x16x32_bf16 v[10:13], v[138:141], v[194:197], v[10:13]
	v_mfma_f32_16x16x32_bf16 v[62:65], v[134:137], v[150:153], v[62:65]
	v_mfma_f32_16x16x32_bf16 v[58:61], v[142:145], v[150:153], v[58:61]
	v_mfma_f32_16x16x32_bf16 v[46:49], v[134:137], v[158:161], v[46:49]
	v_mfma_f32_16x16x32_bf16 v[42:45], v[142:145], v[158:161], v[42:45]
	v_mfma_f32_16x16x32_bf16 v[30:33], v[134:137], v[166:169], v[30:33]
	v_mfma_f32_16x16x32_bf16 v[26:29], v[142:145], v[166:169], v[26:29]
	v_mfma_f32_16x16x32_bf16 v[14:17], v[134:137], v[198:201], v[14:17]
	v_mfma_f32_16x16x32_bf16 v[10:13], v[142:145], v[198:201], v[10:13]
	s_setprio 0
	s_barrier
	s_add_u32 s6, s6, 0xb0080
	s_addc_u32 s7, s7, 0
	s_add_i32 s8, s8, s56
	v_lshl_add_u64 v[130:131], s[6:7], 0, v[176:177]
	s_mov_b32 m0, s8
	s_nop 0
	global_load_lds_dwordx4 v[130:131], off
	v_lshl_add_u64 v[130:131], s[6:7], 0, v[180:181]
	s_add_i32 m0, s8, 0x2000
	s_nop 0
	global_load_lds_dwordx4 v[130:131], off
	s_waitcnt vmcnt(6)
	s_barrier
	s_setprio 1
	v_mfma_f32_16x16x32_bf16 v[54:57], v[202:205], v[146:149], v[54:57]
	v_mfma_f32_16x16x32_bf16 v[50:53], v[210:213], v[146:149], v[50:53]
	v_mfma_f32_16x16x32_bf16 v[38:41], v[202:205], v[154:157], v[38:41]
	v_mfma_f32_16x16x32_bf16 v[34:37], v[210:213], v[154:157], v[34:37]
	v_mfma_f32_16x16x32_bf16 v[22:25], v[202:205], v[162:165], v[22:25]
	v_mfma_f32_16x16x32_bf16 v[18:21], v[210:213], v[162:165], v[18:21]
	v_mfma_f32_16x16x32_bf16 v[6:9], v[202:205], v[194:197], v[6:9]
	v_mfma_f32_16x16x32_bf16 v[2:5], v[210:213], v[194:197], v[2:5]
	v_mfma_f32_16x16x32_bf16 v[54:57], v[206:209], v[150:153], v[54:57]
	v_mfma_f32_16x16x32_bf16 v[50:53], v[214:217], v[150:153], v[50:53]
	v_mfma_f32_16x16x32_bf16 v[38:41], v[206:209], v[158:161], v[38:41]
	v_mfma_f32_16x16x32_bf16 v[34:37], v[214:217], v[158:161], v[34:37]
	v_mfma_f32_16x16x32_bf16 v[22:25], v[206:209], v[166:169], v[22:25]
	v_mfma_f32_16x16x32_bf16 v[18:21], v[214:217], v[166:169], v[18:21]
	v_mfma_f32_16x16x32_bf16 v[6:9], v[206:209], v[198:201], v[6:9]
	v_mfma_f32_16x16x32_bf16 v[2:5], v[214:217], v[198:201], v[2:5]
	s_setprio 0
	s_add_i32 s49, s49, 2
	s_add_u32 s0, s0, 0x100
	s_addc_u32 s1, s1, 0
	s_add_u32 s10, s10, 0x100
	s_addc_u32 s11, s11, 0
	s_cmp_gt_u32 s49, 41
	s_barrier

.LBB0_868:
	s_add_u32 s12, s12, 0xb0080
	s_addc_u32 s13, s13, 0
	s_add_u32 s78, s14, 0x100
	s_addc_u32 s79, s15, 0
	s_mov_b32 s87, -2
	ds_read_b128 v[146:149], v142
	ds_read_b128 v[150:153], v142 offset:1024
	ds_read_b128 v[154:157], v142 offset:2048
	ds_read_b128 v[158:161], v142 offset:3072
	s_add_u32 s14, s12, 0xfff50080
	s_addc_u32 s15, s13, -1
	s_cmp_eq_u32 s87, 18
	s_cselect_b32 s17, s1, s15
	s_cselect_b32 s16, s0, s14
	s_cselect_b32 s15, s7, s79
	s_cselect_b32 s14, s6, s78
	s_mov_b32 m0, s68
	v_lshl_add_u64 v[208:209], s[12:13], 0, v[132:133]
	ds_read_b128 v[162:165], v143
	ds_read_b128 v[166:169], v143 offset:1024
	ds_read_b128 v[184:187], v143 offset:2048
	ds_read_b128 v[188:191], v143 offset:3072
	ds_read_b128 v[192:195], v143 offset:4096
	ds_read_b128 v[196:199], v143 offset:5120
	ds_read_b128 v[200:203], v143 offset:6144
	ds_read_b128 v[204:207], v143 offset:7168
	global_load_lds_dwordx4 v[208:209], off
	v_lshl_add_u64 v[208:209], s[12:13], 0, v[134:135]
	s_mov_b32 m0, s69
	s_nop 0
	global_load_lds_dwordx4 v[208:209], off
	s_waitcnt lgkmcnt(8)
	s_barrier
	s_waitcnt lgkmcnt(0)
	s_setprio 1
	s_waitcnt lgkmcnt(0)
	v_mfma_f32_16x16x32_bf16 v[126:129], v[146:149], v[162:165], 0
	v_mfma_f32_16x16x32_bf16 v[122:125], v[154:157], v[162:165], 0
	v_mfma_f32_16x16x32_bf16 v[118:121], v[146:149], v[184:187], 0
	v_mfma_f32_16x16x32_bf16 v[114:117], v[154:157], v[184:187], 0
	v_mfma_f32_16x16x32_bf16 v[102:105], v[146:149], v[192:195], 0
	v_mfma_f32_16x16x32_bf16 v[98:101], v[154:157], v[192:195], 0
	v_mfma_f32_16x16x32_bf16 v[86:89], v[146:149], v[200:203], 0
	v_mfma_f32_16x16x32_bf16 v[82:85], v[154:157], v[200:203], 0
	v_mfma_f32_16x16x32_bf16 v[126:129], v[150:153], v[166:169], v[126:129]
	v_mfma_f32_16x16x32_bf16 v[122:125], v[158:161], v[166:169], v[122:125]
	v_mfma_f32_16x16x32_bf16 v[118:121], v[150:153], v[188:191], v[118:121]
	v_mfma_f32_16x16x32_bf16 v[114:117], v[158:161], v[188:191], v[114:117]
	v_mfma_f32_16x16x32_bf16 v[102:105], v[150:153], v[196:199], v[102:105]
	v_mfma_f32_16x16x32_bf16 v[98:101], v[158:161], v[196:199], v[98:101]
	v_mfma_f32_16x16x32_bf16 v[86:89], v[150:153], v[204:207], v[86:89]
	v_mfma_f32_16x16x32_bf16 v[82:85], v[158:161], v[204:207], v[82:85]
	s_setprio 0
	s_barrier
	s_mov_b32 m0, s70
	v_lshl_add_u64 v[224:225], s[14:15], 0, v[176:177]
	ds_read_b128 v[208:211], v144
	ds_read_b128 v[212:215], v144 offset:1024
	ds_read_b128 v[216:219], v144 offset:2048
	ds_read_b128 v[220:223], v144 offset:3072
	global_load_lds_dwordx4 v[224:225], off
	v_lshl_add_u64 v[226:227], s[14:15], 0, v[180:181]
	s_mov_b32 m0, s71
	s_nop 0
	global_load_lds_dwordx4 v[226:227], off
	s_barrier
	s_waitcnt lgkmcnt(0)
	s_setprio 1
	s_waitcnt lgkmcnt(0)
	v_mfma_f32_16x16x32_bf16 v[110:113], v[208:211], v[162:165], 0
	v_mfma_f32_16x16x32_bf16 v[106:109], v[216:219], v[162:165], 0
	v_mfma_f32_16x16x32_bf16 v[94:97], v[208:211], v[184:187], 0
	v_mfma_f32_16x16x32_bf16 v[90:93], v[216:219], v[184:187], 0
	v_mfma_f32_16x16x32_bf16 v[78:81], v[208:211], v[192:195], 0
	v_mfma_f32_16x16x32_bf16 v[74:77], v[216:219], v[192:195], 0
	v_mfma_f32_16x16x32_bf16 v[70:73], v[208:211], v[200:203], 0
	v_mfma_f32_16x16x32_bf16 v[66:69], v[216:219], v[200:203], 0
	v_mfma_f32_16x16x32_bf16 v[110:113], v[212:215], v[166:169], v[110:113]
	v_mfma_f32_16x16x32_bf16 v[106:109], v[220:223], v[166:169], v[106:109]
	v_mfma_f32_16x16x32_bf16 v[94:97], v[212:215], v[188:191], v[94:97]
	v_mfma_f32_16x16x32_bf16 v[90:93], v[220:223], v[188:191], v[90:93]
	v_mfma_f32_16x16x32_bf16 v[78:81], v[212:215], v[196:199], v[78:81]
	v_mfma_f32_16x16x32_bf16 v[74:77], v[220:223], v[196:199], v[74:77]
	v_mfma_f32_16x16x32_bf16 v[70:73], v[212:215], v[204:207], v[70:73]
	v_mfma_f32_16x16x32_bf16 v[66:69], v[220:223], v[204:207], v[66:69]
	s_setprio 0
	s_mov_b32 m0, s40
	v_lshl_add_u64 v[228:229], s[16:17], 0, v[172:173]
	s_barrier
	ds_read_b128 v[162:165], v143 offset:16384
	ds_read_b128 v[166:169], v143 offset:17408
	ds_read_b128 v[184:187], v143 offset:18432
	ds_read_b128 v[188:191], v143 offset:19456
	ds_read_b128 v[192:195], v143 offset:20480
	ds_read_b128 v[196:199], v143 offset:21504
	ds_read_b128 v[200:203], v143 offset:22528
	ds_read_b128 v[204:207], v143 offset:23552
	global_load_lds_dwordx4 v[228:229], off
	v_lshl_add_u64 v[234:235], s[16:17], 0, v[178:179]
	s_mov_b32 m0, s41
	s_nop 0
	global_load_lds_dwordx4 v[234:235], off
	s_barrier
	s_waitcnt lgkmcnt(0)
	s_setprio 1
	s_waitcnt lgkmcnt(0)
	v_mfma_f32_16x16x32_bf16 v[62:65], v[146:149], v[162:165], 0
	v_mfma_f32_16x16x32_bf16 v[58:61], v[154:157], v[162:165], 0
	v_mfma_f32_16x16x32_bf16 v[54:57], v[146:149], v[184:187], 0
	v_mfma_f32_16x16x32_bf16 v[50:53], v[154:157], v[184:187], 0
	v_mfma_f32_16x16x32_bf16 v[38:41], v[146:149], v[192:195], 0
	v_mfma_f32_16x16x32_bf16 v[34:37], v[154:157], v[192:195], 0
	v_mfma_f32_16x16x32_bf16 v[22:25], v[146:149], v[200:203], 0
	v_mfma_f32_16x16x32_bf16 v[18:21], v[154:157], v[200:203], 0
	v_mfma_f32_16x16x32_bf16 v[62:65], v[150:153], v[166:169], v[62:65]
	v_mfma_f32_16x16x32_bf16 v[58:61], v[158:161], v[166:169], v[58:61]
	v_mfma_f32_16x16x32_bf16 v[54:57], v[150:153], v[188:191], v[54:57]
	v_mfma_f32_16x16x32_bf16 v[50:53], v[158:161], v[188:191], v[50:53]
	v_mfma_f32_16x16x32_bf16 v[38:41], v[150:153], v[196:199], v[38:41]
	v_mfma_f32_16x16x32_bf16 v[34:37], v[158:161], v[196:199], v[34:37]
	v_mfma_f32_16x16x32_bf16 v[22:25], v[150:153], v[204:207], v[22:25]
	v_mfma_f32_16x16x32_bf16 v[18:21], v[158:161], v[204:207], v[18:21]
	s_setprio 0
	s_barrier
	s_add_u32 s20, s14, 0xb0000
	s_addc_u32 s21, s15, 0
	s_add_i32 s60, s56, s35
	v_lshl_add_u64 v[146:147], s[20:21], 0, v[176:177]
	s_mov_b32 m0, s60
	s_nop 0
	global_load_lds_dwordx4 v[146:147], off
	v_lshl_add_u64 v[146:147], s[20:21], 0, v[180:181]
	s_add_i32 m0, s60, 0x2000
	s_nop 0
	global_load_lds_dwordx4 v[146:147], off
	s_waitcnt vmcnt(6)
	s_barrier
	s_setprio 1
	v_mfma_f32_16x16x32_bf16 v[46:49], v[208:211], v[162:165], 0
	v_mfma_f32_16x16x32_bf16 v[42:45], v[216:219], v[162:165], 0
	v_mfma_f32_16x16x32_bf16 v[30:33], v[208:211], v[184:187], 0
	v_mfma_f32_16x16x32_bf16 v[26:29], v[216:219], v[184:187], 0
	v_mfma_f32_16x16x32_bf16 v[14:17], v[208:211], v[192:195], 0
	v_mfma_f32_16x16x32_bf16 v[10:13], v[216:219], v[192:195], 0
	v_mfma_f32_16x16x32_bf16 v[6:9], v[208:211], v[200:203], 0
	v_mfma_f32_16x16x32_bf16 v[2:5], v[216:219], v[200:203], 0
	v_mfma_f32_16x16x32_bf16 v[46:49], v[212:215], v[166:169], v[46:49]
	v_mfma_f32_16x16x32_bf16 v[42:45], v[220:223], v[166:169], v[42:45]
	v_mfma_f32_16x16x32_bf16 v[30:33], v[212:215], v[188:191], v[30:33]
	v_mfma_f32_16x16x32_bf16 v[26:29], v[220:223], v[188:191], v[26:29]
	v_mfma_f32_16x16x32_bf16 v[14:17], v[212:215], v[196:199], v[14:17]
	v_mfma_f32_16x16x32_bf16 v[10:13], v[220:223], v[196:199], v[10:13]
	v_mfma_f32_16x16x32_bf16 v[6:9], v[212:215], v[204:207], v[6:9]
	v_mfma_f32_16x16x32_bf16 v[2:5], v[220:223], v[204:207], v[2:5]
	s_setprio 0
	s_add_i32 s20, 0, 0x18000
	v_add_u32_e32 v145, s20, v141
	s_barrier
	ds_read_b128 v[146:149], v145
	ds_read_b128 v[150:153], v145 offset:1024
	ds_read_b128 v[154:157], v145 offset:2048
	ds_read_b128 v[158:161], v145 offset:3072
	s_add_u32 s16, s16, 0xb0000
	s_addc_u32 s17, s17, 0
	s_mov_b32 m0, s48
	v_lshl_add_u64 v[208:209], s[16:17], 0, v[172:173]
	ds_read_b128 v[162:165], v143 offset:32768
	ds_read_b128 v[166:169], v143 offset:33792
	ds_read_b128 v[184:187], v143 offset:34816
	ds_read_b128 v[188:191], v143 offset:35840
	ds_read_b128 v[192:195], v143 offset:36864
	ds_read_b128 v[196:199], v143 offset:37888
	ds_read_b128 v[200:203], v143 offset:38912
	ds_read_b128 v[204:207], v143 offset:39936
	global_load_lds_dwordx4 v[208:209], off
	v_lshl_add_u64 v[208:209], s[16:17], 0, v[178:179]
	s_mov_b32 m0, s49
	s_nop 0
	global_load_lds_dwordx4 v[208:209], off
	s_waitcnt lgkmcnt(8)
	s_barrier
	s_waitcnt lgkmcnt(0)
	s_setprio 1
	s_waitcnt lgkmcnt(0)
	v_mfma_f32_16x16x32_bf16 v[126:129], v[146:149], v[162:165], v[126:129]
	v_mfma_f32_16x16x32_bf16 v[122:125], v[154:157], v[162:165], v[122:125]
	v_mfma_f32_16x16x32_bf16 v[118:121], v[146:149], v[184:187], v[118:121]
	v_mfma_f32_16x16x32_bf16 v[114:117], v[154:157], v[184:187], v[114:117]
	v_mfma_f32_16x16x32_bf16 v[102:105], v[146:149], v[192:195], v[102:105]
	v_mfma_f32_16x16x32_bf16 v[98:101], v[154:157], v[192:195], v[98:101]
	v_mfma_f32_16x16x32_bf16 v[86:89], v[146:149], v[200:203], v[86:89]
	v_mfma_f32_16x16x32_bf16 v[82:85], v[154:157], v[200:203], v[82:85]
	v_mfma_f32_16x16x32_bf16 v[126:129], v[150:153], v[166:169], v[126:129]
	v_mfma_f32_16x16x32_bf16 v[122:125], v[158:161], v[166:169], v[122:125]
	v_mfma_f32_16x16x32_bf16 v[118:121], v[150:153], v[188:191], v[118:121]
	v_mfma_f32_16x16x32_bf16 v[114:117], v[158:161], v[188:191], v[114:117]
	v_mfma_f32_16x16x32_bf16 v[102:105], v[150:153], v[196:199], v[102:105]
	v_mfma_f32_16x16x32_bf16 v[98:101], v[158:161], v[196:199], v[98:101]
	v_mfma_f32_16x16x32_bf16 v[86:89], v[150:153], v[204:207], v[86:89]
	v_mfma_f32_16x16x32_bf16 v[82:85], v[158:161], v[204:207], v[82:85]
	s_setprio 0
	s_barrier
	s_add_i32 s16, 0, 0x1c000
	s_add_i32 s17, s20, s35
	v_add_u32_e32 v145, s16, v141
	v_lshl_add_u64 v[224:225], v[224:225], 0, s[8:9]
	s_mov_b32 m0, s17
	ds_read_b128 v[208:211], v145
	ds_read_b128 v[212:215], v145 offset:1024
	ds_read_b128 v[216:219], v145 offset:2048
	ds_read_b128 v[220:223], v145 offset:3072
	global_load_lds_dwordx4 v[224:225], off
	v_lshl_add_u64 v[224:225], v[226:227], 0, s[8:9]
	s_add_i32 m0, s17, 0x2000
	s_nop 0
	global_load_lds_dwordx4 v[224:225], off
	s_barrier
	s_waitcnt lgkmcnt(0)
	s_setprio 1
	s_waitcnt lgkmcnt(0)
	v_mfma_f32_16x16x32_bf16 v[110:113], v[208:211], v[162:165], v[110:113]
	v_mfma_f32_16x16x32_bf16 v[106:109], v[216:219], v[162:165], v[106:109]
	v_mfma_f32_16x16x32_bf16 v[94:97], v[208:211], v[184:187], v[94:97]
	v_mfma_f32_16x16x32_bf16 v[90:93], v[216:219], v[184:187], v[90:93]
	v_mfma_f32_16x16x32_bf16 v[78:81], v[208:211], v[192:195], v[78:81]
	v_mfma_f32_16x16x32_bf16 v[74:77], v[216:219], v[192:195], v[74:77]
	v_mfma_f32_16x16x32_bf16 v[70:73], v[208:211], v[200:203], v[70:73]
	v_mfma_f32_16x16x32_bf16 v[66:69], v[216:219], v[200:203], v[66:69]
	v_mfma_f32_16x16x32_bf16 v[110:113], v[212:215], v[166:169], v[110:113]
	v_mfma_f32_16x16x32_bf16 v[106:109], v[220:223], v[166:169], v[106:109]
	v_mfma_f32_16x16x32_bf16 v[94:97], v[212:215], v[188:191], v[94:97]
	v_mfma_f32_16x16x32_bf16 v[90:93], v[220:223], v[188:191], v[90:93]
	v_mfma_f32_16x16x32_bf16 v[78:81], v[212:215], v[196:199], v[78:81]
	v_mfma_f32_16x16x32_bf16 v[74:77], v[220:223], v[196:199], v[74:77]
	v_mfma_f32_16x16x32_bf16 v[70:73], v[212:215], v[204:207], v[70:73]
	v_mfma_f32_16x16x32_bf16 v[66:69], v[220:223], v[204:207], v[66:69]
	s_setprio 0
	s_mov_b32 m0, s54
	v_lshl_add_u64 v[224:225], v[228:229], 0, s[8:9]
	s_barrier
	ds_read_b128 v[162:165], v143 offset:49152
	ds_read_b128 v[166:169], v143 offset:50176
	ds_read_b128 v[184:187], v143 offset:51200
	ds_read_b128 v[188:191], v143 offset:52224
	ds_read_b128 v[192:195], v143 offset:53248
	ds_read_b128 v[196:199], v143 offset:54272
	ds_read_b128 v[200:203], v143 offset:55296
	ds_read_b128 v[204:207], v143 offset:56320
	global_load_lds_dwordx4 v[224:225], off
	v_lshl_add_u64 v[224:225], v[234:235], 0, s[8:9]
	s_mov_b32 m0, s55
	s_nop 0
	global_load_lds_dwordx4 v[224:225], off
	s_barrier
	s_waitcnt lgkmcnt(0)
	s_setprio 1
	s_waitcnt lgkmcnt(0)
	v_mfma_f32_16x16x32_bf16 v[62:65], v[146:149], v[162:165], v[62:65]
	v_mfma_f32_16x16x32_bf16 v[58:61], v[154:157], v[162:165], v[58:61]
	v_mfma_f32_16x16x32_bf16 v[54:57], v[146:149], v[184:187], v[54:57]
	v_mfma_f32_16x16x32_bf16 v[50:53], v[154:157], v[184:187], v[50:53]
	v_mfma_f32_16x16x32_bf16 v[38:41], v[146:149], v[192:195], v[38:41]
	v_mfma_f32_16x16x32_bf16 v[34:37], v[154:157], v[192:195], v[34:37]
	v_mfma_f32_16x16x32_bf16 v[22:25], v[146:149], v[200:203], v[22:25]
	v_mfma_f32_16x16x32_bf16 v[18:21], v[154:157], v[200:203], v[18:21]
	v_mfma_f32_16x16x32_bf16 v[62:65], v[150:153], v[166:169], v[62:65]
	v_mfma_f32_16x16x32_bf16 v[58:61], v[158:161], v[166:169], v[58:61]
	v_mfma_f32_16x16x32_bf16 v[54:57], v[150:153], v[188:191], v[54:57]
	v_mfma_f32_16x16x32_bf16 v[50:53], v[158:161], v[188:191], v[50:53]
	v_mfma_f32_16x16x32_bf16 v[38:41], v[150:153], v[196:199], v[38:41]
	v_mfma_f32_16x16x32_bf16 v[34:37], v[158:161], v[196:199], v[34:37]
	v_mfma_f32_16x16x32_bf16 v[22:25], v[150:153], v[204:207], v[22:25]
	v_mfma_f32_16x16x32_bf16 v[18:21], v[158:161], v[204:207], v[18:21]
	s_setprio 0
	s_barrier
	s_add_u32 s14, s14, 0xb0080
	s_addc_u32 s15, s15, 0
	s_add_i32 s16, s16, s35
	v_lshl_add_u64 v[146:147], s[14:15], 0, v[176:177]
	s_mov_b32 m0, s16
	s_nop 0
	global_load_lds_dwordx4 v[146:147], off
	v_lshl_add_u64 v[146:147], s[14:15], 0, v[180:181]
	s_add_i32 m0, s16, 0x2000
	s_nop 0
	global_load_lds_dwordx4 v[146:147], off
	s_waitcnt vmcnt(6)
	s_barrier
	s_setprio 1
	v_mfma_f32_16x16x32_bf16 v[46:49], v[208:211], v[162:165], v[46:49]
	v_mfma_f32_16x16x32_bf16 v[42:45], v[216:219], v[162:165], v[42:45]
	v_mfma_f32_16x16x32_bf16 v[30:33], v[208:211], v[184:187], v[30:33]
	v_mfma_f32_16x16x32_bf16 v[26:29], v[216:219], v[184:187], v[26:29]
	v_mfma_f32_16x16x32_bf16 v[14:17], v[208:211], v[192:195], v[14:17]
	v_mfma_f32_16x16x32_bf16 v[10:13], v[216:219], v[192:195], v[10:13]
	v_mfma_f32_16x16x32_bf16 v[6:9], v[208:211], v[200:203], v[6:9]
	v_mfma_f32_16x16x32_bf16 v[2:5], v[216:219], v[200:203], v[2:5]
	v_mfma_f32_16x16x32_bf16 v[46:49], v[212:215], v[166:169], v[46:49]
	v_mfma_f32_16x16x32_bf16 v[42:45], v[220:223], v[166:169], v[42:45]
	v_mfma_f32_16x16x32_bf16 v[30:33], v[212:215], v[188:191], v[30:33]
	v_mfma_f32_16x16x32_bf16 v[26:29], v[220:223], v[188:191], v[26:29]
	v_mfma_f32_16x16x32_bf16 v[14:17], v[212:215], v[196:199], v[14:17]
	v_mfma_f32_16x16x32_bf16 v[10:13], v[220:223], v[196:199], v[10:13]
	v_mfma_f32_16x16x32_bf16 v[6:9], v[212:215], v[204:207], v[6:9]
	v_mfma_f32_16x16x32_bf16 v[2:5], v[220:223], v[204:207], v[2:5]
	s_setprio 0
	s_add_i32 s87, s87, 2
	s_add_u32 s12, s12, 0x100
	s_addc_u32 s13, s13, 0
	s_add_u32 s78, s78, 0x100
	s_addc_u32 s79, s79, 0
	s_cmp_gt_u32 s87, 19
	s_barrier

.LBB0_1374:
	s_ashr_i32 s41, s40, 31
	s_xor_b64 s[50:51], s[18:19], -1
	s_lshl_b64 s[20:21], s[40:41], 19
	s_add_u32 s48, s65, s20
	s_addc_u32 s49, s66, s21
	s_and_b64 s[20:21], s[18:19], exec
	s_cselect_b32 s3, s49, s35
	s_cselect_b32 s5, s48, s34
	s_ashr_i32 s39, s38, 31
	s_lshl_b64 s[20:21], s[38:39], 19
	s_add_u32 s52, s67, s20
	s_addc_u32 s53, s68, s21
	s_and_b64 s[18:19], s[18:19], exec
	s_cselect_b32 s39, s53, s55
	s_cselect_b32 s41, s52, s54
	s_add_u32 s34, s34, 0x40080
	s_addc_u32 s35, s35, 0
	s_add_u32 s56, s54, 0x100
	s_addc_u32 s57, s55, 0
	s_mov_b32 vcc_lo, -2
	s_waitcnt vmcnt(0)
	ds_read_b128 v[10:13], v225
	ds_read_b128 v[14:17], v225 offset:1024
	ds_read_b128 v[26:29], v225 offset:2048
	ds_read_b128 v[30:33], v225 offset:3072
	s_add_u32 s18, s34, 0xfffc0080
	s_addc_u32 s19, s35, -1
	s_cmp_eq_u32 vcc_lo, 12
	s_cselect_b32 s19, s3, s19
	s_cselect_b32 s18, s5, s18
	s_cselect_b32 s55, s39, s57
	s_cselect_b32 s54, s41, s56
	v_lshl_add_u64 v[202:203], s[34:35], 0, v[178:179]
	s_add_i32 m0, s72, 0xc000
	ds_read_b128 v[34:37], v226
	ds_read_b128 v[38:41], v226 offset:1024
	ds_read_b128 v[50:53], v226 offset:2048
	ds_read_b128 v[54:57], v226 offset:3072
	ds_read_b128 v[186:189], v226 offset:4096
	ds_read_b128 v[190:193], v226 offset:5120
	ds_read_b128 v[194:197], v226 offset:6144
	ds_read_b128 v[198:201], v226 offset:7168
	global_load_lds_dwordx4 v[202:203], off
	v_lshl_add_u64 v[202:203], s[34:35], 0, v[180:181]
	s_add_i32 m0, s72, 0xe000
	s_nop 0
	global_load_lds_dwordx4 v[202:203], off
	s_waitcnt lgkmcnt(8)
	s_barrier
	s_waitcnt lgkmcnt(0)
	s_setprio 1
	s_waitcnt lgkmcnt(0)
	v_mfma_f32_16x16x32_bf16 v[158:161], v[10:13], v[34:37], 0
	v_mfma_f32_16x16x32_bf16 v[154:157], v[26:29], v[34:37], 0
	v_mfma_f32_16x16x32_bf16 v[142:145], v[10:13], v[50:53], 0
	v_mfma_f32_16x16x32_bf16 v[138:141], v[26:29], v[50:53], 0
	v_mfma_f32_16x16x32_bf16 v[126:129], v[10:13], v[186:189], 0
	v_mfma_f32_16x16x32_bf16 v[122:125], v[26:29], v[186:189], 0
	v_mfma_f32_16x16x32_bf16 v[110:113], v[10:13], v[194:197], 0
	v_mfma_f32_16x16x32_bf16 v[106:109], v[26:29], v[194:197], 0
	v_mfma_f32_16x16x32_bf16 v[158:161], v[14:17], v[38:41], v[158:161]
	v_mfma_f32_16x16x32_bf16 v[154:157], v[30:33], v[38:41], v[154:157]
	v_mfma_f32_16x16x32_bf16 v[142:145], v[14:17], v[54:57], v[142:145]
	v_mfma_f32_16x16x32_bf16 v[138:141], v[30:33], v[54:57], v[138:141]
	v_mfma_f32_16x16x32_bf16 v[126:129], v[14:17], v[190:193], v[126:129]
	v_mfma_f32_16x16x32_bf16 v[122:125], v[30:33], v[190:193], v[122:125]
	v_mfma_f32_16x16x32_bf16 v[110:113], v[14:17], v[198:201], v[110:113]
	v_mfma_f32_16x16x32_bf16 v[106:109], v[30:33], v[198:201], v[106:109]
	s_setprio 0
	s_barrier
	s_add_i32 s20, s33, s71
	v_lshl_add_u64 v[222:223], s[54:55], 0, v[164:165]
	s_mov_b32 m0, s20
	ds_read_b128 v[202:205], v227
	ds_read_b128 v[206:209], v227 offset:1024
	ds_read_b128 v[210:213], v227 offset:2048
	ds_read_b128 v[214:217], v227 offset:3072
	global_load_lds_dwordx4 v[222:223], off
	v_lshl_add_u64 v[238:239], s[54:55], 0, v[168:169]
	s_add_i32 m0, s20, 0x2000
	s_nop 0
	global_load_lds_dwordx4 v[238:239], off
	s_barrier
	s_waitcnt lgkmcnt(0)
	s_setprio 1
	s_waitcnt lgkmcnt(0)
	v_mfma_f32_16x16x32_bf16 v[150:153], v[202:205], v[34:37], 0
	v_mfma_f32_16x16x32_bf16 v[34:37], v[210:213], v[34:37], 0
	v_mfma_f32_16x16x32_bf16 v[150:153], v[206:209], v[38:41], v[150:153]
	v_mfma_f32_16x16x32_bf16 v[34:37], v[214:217], v[38:41], v[34:37]
	v_mfma_f32_16x16x32_bf16 v[38:41], v[202:205], v[50:53], 0
	v_mfma_f32_16x16x32_bf16 v[50:53], v[210:213], v[50:53], 0
	v_mfma_f32_16x16x32_bf16 v[114:117], v[210:213], v[186:189], 0
	v_mfma_f32_16x16x32_bf16 v[102:105], v[202:205], v[194:197], 0
	v_mfma_f32_16x16x32_bf16 v[98:101], v[210:213], v[194:197], 0
	v_mfma_f32_16x16x32_bf16 v[38:41], v[206:209], v[54:57], v[38:41]
	v_mfma_f32_16x16x32_bf16 v[50:53], v[214:217], v[54:57], v[50:53]
	v_mfma_f32_16x16x32_bf16 v[54:57], v[202:205], v[186:189], 0
	v_mfma_f32_16x16x32_bf16 v[114:117], v[214:217], v[190:193], v[114:117]
	v_mfma_f32_16x16x32_bf16 v[102:105], v[206:209], v[198:201], v[102:105]
	v_mfma_f32_16x16x32_bf16 v[98:101], v[214:217], v[198:201], v[98:101]
	v_mfma_f32_16x16x32_bf16 v[54:57], v[206:209], v[190:193], v[54:57]
	s_setprio 0
	s_mov_b32 m0, s72
	v_lshl_add_u64 v[240:241], s[18:19], 0, v[162:163]
	s_barrier
	ds_read_b128 v[118:121], v226 offset:16384
	ds_read_b128 v[130:133], v226 offset:17408
	ds_read_b128 v[134:137], v226 offset:18432
	ds_read_b128 v[146:149], v226 offset:19456
	ds_read_b128 v[186:189], v226 offset:20480
	ds_read_b128 v[190:193], v226 offset:21504
	ds_read_b128 v[194:197], v226 offset:22528
	ds_read_b128 v[198:201], v226 offset:23552
	global_load_lds_dwordx4 v[240:241], off
	v_lshl_add_u64 v[242:243], s[18:19], 0, v[166:167]
	s_mov_b32 m0, s73
	s_nop 0
	global_load_lds_dwordx4 v[242:243], off
	s_barrier
	s_waitcnt lgkmcnt(0)
	s_setprio 1
	s_waitcnt lgkmcnt(0)
	v_mfma_f32_16x16x32_bf16 v[94:97], v[10:13], v[118:121], 0
	v_mfma_f32_16x16x32_bf16 v[90:93], v[26:29], v[118:121], 0
	v_mfma_f32_16x16x32_bf16 v[78:81], v[10:13], v[134:137], 0
	v_mfma_f32_16x16x32_bf16 v[74:77], v[26:29], v[134:137], 0
	v_mfma_f32_16x16x32_bf16 v[62:65], v[10:13], v[186:189], 0
	v_mfma_f32_16x16x32_bf16 v[58:61], v[26:29], v[186:189], 0
	v_mfma_f32_16x16x32_bf16 v[10:13], v[10:13], v[194:197], 0
	v_mfma_f32_16x16x32_bf16 v[94:97], v[14:17], v[130:133], v[94:97]
	v_mfma_f32_16x16x32_bf16 v[90:93], v[30:33], v[130:133], v[90:93]
	v_mfma_f32_16x16x32_bf16 v[78:81], v[14:17], v[146:149], v[78:81]
	v_mfma_f32_16x16x32_bf16 v[74:77], v[30:33], v[146:149], v[74:77]
	v_mfma_f32_16x16x32_bf16 v[62:65], v[14:17], v[190:193], v[62:65]
	v_mfma_f32_16x16x32_bf16 v[58:61], v[30:33], v[190:193], v[58:61]
	v_mfma_f32_16x16x32_bf16 v[10:13], v[14:17], v[198:201], v[10:13]
	v_mfma_f32_16x16x32_bf16 v[14:17], v[26:29], v[194:197], 0
	v_mfma_f32_16x16x32_bf16 v[14:17], v[30:33], v[198:201], v[14:17]
	s_setprio 0
	s_barrier
	s_add_u32 s20, s54, 0x40000
	s_addc_u32 s21, s55, 0
	s_add_i32 s60, s64, s71
	v_lshl_add_u64 v[18:19], s[20:21], 0, v[164:165]
	s_mov_b32 m0, s60
	s_nop 0
	global_load_lds_dwordx4 v[18:19], off
	v_lshl_add_u64 v[18:19], s[20:21], 0, v[168:169]
	s_add_i32 m0, s60, 0x2000
	s_nop 0
	global_load_lds_dwordx4 v[18:19], off
	s_waitcnt vmcnt(6)
	s_barrier
	s_setprio 1
	v_mfma_f32_16x16x32_bf16 v[18:21], v[202:205], v[118:121], 0
	v_mfma_f32_16x16x32_bf16 v[26:29], v[206:209], v[130:133], v[18:21]
	v_mfma_f32_16x16x32_bf16 v[18:21], v[210:213], v[118:121], 0
	v_mfma_f32_16x16x32_bf16 v[30:33], v[214:217], v[130:133], v[18:21]
	v_mfma_f32_16x16x32_bf16 v[18:21], v[202:205], v[134:137], 0
	v_mfma_f32_16x16x32_bf16 v[70:73], v[206:209], v[146:149], v[18:21]
	v_mfma_f32_16x16x32_bf16 v[18:21], v[210:213], v[134:137], 0
	v_mfma_f32_16x16x32_bf16 v[66:69], v[214:217], v[146:149], v[18:21]
	v_mfma_f32_16x16x32_bf16 v[18:21], v[202:205], v[186:189], 0
	v_mfma_f32_16x16x32_bf16 v[46:49], v[206:209], v[190:193], v[18:21]
	v_mfma_f32_16x16x32_bf16 v[18:21], v[210:213], v[186:189], 0
	v_mfma_f32_16x16x32_bf16 v[6:9], v[202:205], v[194:197], 0
	v_mfma_f32_16x16x32_bf16 v[2:5], v[210:213], v[194:197], 0
	v_mfma_f32_16x16x32_bf16 v[42:45], v[214:217], v[190:193], v[18:21]
	v_mfma_f32_16x16x32_bf16 v[6:9], v[206:209], v[198:201], v[6:9]
	v_mfma_f32_16x16x32_bf16 v[2:5], v[214:217], v[198:201], v[2:5]
	s_setprio 0
	s_add_i32 s20, 0, 0x18000
	v_add_u32_e32 v86, s20, v175
	s_barrier
	ds_read_b128 v[18:21], v86
	ds_read_b128 v[22:25], v86 offset:1024
	ds_read_b128 v[82:85], v86 offset:2048
	ds_read_b128 v[86:89], v86 offset:3072
	s_add_u32 s18, s18, 0x40000
	s_addc_u32 s19, s19, 0
	s_mov_b32 m0, s74
	v_lshl_add_u64 v[134:135], s[18:19], 0, v[162:163]
	ds_read_b128 v[118:121], v226 offset:32768
	ds_read_b128 v[130:133], v226 offset:33792
	ds_read_b128 v[186:189], v226 offset:34816
	ds_read_b128 v[190:193], v226 offset:35840
	ds_read_b128 v[194:197], v226 offset:36864
	ds_read_b128 v[198:201], v226 offset:37888
	ds_read_b128 v[202:205], v226 offset:38912
	ds_read_b128 v[206:209], v226 offset:39936
	global_load_lds_dwordx4 v[134:135], off
	v_lshl_add_u64 v[134:135], s[18:19], 0, v[166:167]
	s_mov_b32 m0, s75
	s_nop 0
	global_load_lds_dwordx4 v[134:135], off
	s_waitcnt lgkmcnt(8)
	s_barrier
	s_waitcnt lgkmcnt(0)
	s_setprio 1
	s_waitcnt lgkmcnt(0)
	v_mfma_f32_16x16x32_bf16 v[134:137], v[18:21], v[118:121], v[158:161]
	v_mfma_f32_16x16x32_bf16 v[158:161], v[22:25], v[130:133], v[134:137]
	v_mfma_f32_16x16x32_bf16 v[134:137], v[82:85], v[118:121], v[154:157]
	v_mfma_f32_16x16x32_bf16 v[154:157], v[86:89], v[130:133], v[134:137]
	v_mfma_f32_16x16x32_bf16 v[134:137], v[18:21], v[186:189], v[142:145]
	v_mfma_f32_16x16x32_bf16 v[142:145], v[22:25], v[190:193], v[134:137]
	v_mfma_f32_16x16x32_bf16 v[134:137], v[82:85], v[186:189], v[138:141]
	v_mfma_f32_16x16x32_bf16 v[126:129], v[18:21], v[194:197], v[126:129]
	v_mfma_f32_16x16x32_bf16 v[122:125], v[82:85], v[194:197], v[122:125]
	v_mfma_f32_16x16x32_bf16 v[110:113], v[18:21], v[202:205], v[110:113]
	v_mfma_f32_16x16x32_bf16 v[106:109], v[82:85], v[202:205], v[106:109]
	v_mfma_f32_16x16x32_bf16 v[138:141], v[86:89], v[190:193], v[134:137]
	v_mfma_f32_16x16x32_bf16 v[126:129], v[22:25], v[198:201], v[126:129]
	v_mfma_f32_16x16x32_bf16 v[122:125], v[86:89], v[198:201], v[122:125]
	v_mfma_f32_16x16x32_bf16 v[110:113], v[22:25], v[206:209], v[110:113]
	v_mfma_f32_16x16x32_bf16 v[106:109], v[86:89], v[206:209], v[106:109]
	s_setprio 0
	s_barrier
	s_add_i32 s21, 0, 0x1c000
	v_add_u32_e32 v134, s21, v175
	s_add_i32 s18, s20, s71
	ds_read_b128 v[210:213], v134
	ds_read_b128 v[214:217], v134 offset:1024
	ds_read_b128 v[218:221], v134 offset:2048
	ds_read_b128 v[234:237], v134 offset:3072
	v_lshl_add_u64 v[134:135], v[222:223], 0, s[24:25]
	s_mov_b32 m0, s18
	s_nop 0
	global_load_lds_dwordx4 v[134:135], off
	v_lshl_add_u64 v[134:135], v[238:239], 0, s[24:25]
	s_add_i32 m0, s18, 0x2000
	s_nop 0
	global_load_lds_dwordx4 v[134:135], off
	s_barrier
	s_waitcnt lgkmcnt(0)
	s_setprio 1
	s_waitcnt lgkmcnt(0)
	v_mfma_f32_16x16x32_bf16 v[34:37], v[218:221], v[118:121], v[34:37]
	v_mfma_f32_16x16x32_bf16 v[134:137], v[210:213], v[118:121], v[150:153]
	v_mfma_f32_16x16x32_bf16 v[146:149], v[234:237], v[130:133], v[34:37]
	v_mfma_f32_16x16x32_bf16 v[34:37], v[210:213], v[186:189], v[38:41]
	v_mfma_f32_16x16x32_bf16 v[150:153], v[214:217], v[130:133], v[134:137]
	v_mfma_f32_16x16x32_bf16 v[134:137], v[214:217], v[190:193], v[34:37]
	v_mfma_f32_16x16x32_bf16 v[34:37], v[218:221], v[186:189], v[50:53]
	v_mfma_f32_16x16x32_bf16 v[130:133], v[234:237], v[190:193], v[34:37]
	v_mfma_f32_16x16x32_bf16 v[34:37], v[210:213], v[194:197], v[54:57]
	v_mfma_f32_16x16x32_bf16 v[118:121], v[214:217], v[198:201], v[34:37]
	v_mfma_f32_16x16x32_bf16 v[34:37], v[218:221], v[194:197], v[114:117]
	v_mfma_f32_16x16x32_bf16 v[114:117], v[234:237], v[198:201], v[34:37]
	v_mfma_f32_16x16x32_bf16 v[34:37], v[210:213], v[202:205], v[102:105]
	v_mfma_f32_16x16x32_bf16 v[102:105], v[214:217], v[206:209], v[34:37]
	v_mfma_f32_16x16x32_bf16 v[34:37], v[218:221], v[202:205], v[98:101]
	v_mfma_f32_16x16x32_bf16 v[98:101], v[234:237], v[206:209], v[34:37]
	s_setprio 0
	s_mov_b32 m0, s95
	v_lshl_add_u64 v[202:203], v[240:241], 0, s[24:25]
	s_barrier
	s_nop 2
	ds_read_b128 v[34:37], v226 offset:49152
	ds_read_b128 v[38:41], v226 offset:50176
	ds_read_b128 v[50:53], v226 offset:51200
	ds_read_b128 v[54:57], v226 offset:52224
	ds_read_b128 v[186:189], v226 offset:53248
	ds_read_b128 v[190:193], v226 offset:54272
	ds_read_b128 v[194:197], v226 offset:55296
	ds_read_b128 v[198:201], v226 offset:56320
	global_load_lds_dwordx4 v[202:203], off
	v_lshl_add_u64 v[202:203], v[242:243], 0, s[24:25]
	s_mov_b32 m0, s96
	s_nop 0
	global_load_lds_dwordx4 v[202:203], off
	s_barrier
	s_waitcnt lgkmcnt(0)
	s_setprio 1
	s_waitcnt lgkmcnt(0)
	v_mfma_f32_16x16x32_bf16 v[94:97], v[18:21], v[34:37], v[94:97]
	v_mfma_f32_16x16x32_bf16 v[78:81], v[18:21], v[50:53], v[78:81]
	v_mfma_f32_16x16x32_bf16 v[62:65], v[18:21], v[186:189], v[62:65]
	v_mfma_f32_16x16x32_bf16 v[10:13], v[18:21], v[194:197], v[10:13]
	v_mfma_f32_16x16x32_bf16 v[94:97], v[22:25], v[38:41], v[94:97]
	v_mfma_f32_16x16x32_bf16 v[90:93], v[82:85], v[34:37], v[90:93]
	v_mfma_f32_16x16x32_bf16 v[78:81], v[22:25], v[54:57], v[78:81]
	v_mfma_f32_16x16x32_bf16 v[74:77], v[82:85], v[50:53], v[74:77]
	v_mfma_f32_16x16x32_bf16 v[62:65], v[22:25], v[190:193], v[62:65]
	v_mfma_f32_16x16x32_bf16 v[58:61], v[82:85], v[186:189], v[58:61]
	v_mfma_f32_16x16x32_bf16 v[22:25], v[22:25], v[198:201], v[10:13]
	v_mfma_f32_16x16x32_bf16 v[10:13], v[82:85], v[194:197], v[14:17]
	v_mfma_f32_16x16x32_bf16 v[90:93], v[86:89], v[38:41], v[90:93]
	v_mfma_f32_16x16x32_bf16 v[74:77], v[86:89], v[54:57], v[74:77]
	v_mfma_f32_16x16x32_bf16 v[58:61], v[86:89], v[190:193], v[58:61]
	v_mfma_f32_16x16x32_bf16 v[18:21], v[86:89], v[198:201], v[10:13]
	s_setprio 0
	s_barrier
	s_add_u32 s18, s54, 0x40080
	s_addc_u32 s19, s55, 0
	s_add_i32 s20, s21, s71
	v_lshl_add_u64 v[10:11], s[18:19], 0, v[164:165]
	s_mov_b32 m0, s20
	s_nop 0
	global_load_lds_dwordx4 v[10:11], off
	v_lshl_add_u64 v[10:11], s[18:19], 0, v[168:169]
	s_add_i32 m0, s20, 0x2000
	s_nop 0
	global_load_lds_dwordx4 v[10:11], off
	s_waitcnt vmcnt(6)
	s_barrier
	s_setprio 1
	v_mfma_f32_16x16x32_bf16 v[10:13], v[210:213], v[34:37], v[26:29]
	v_mfma_f32_16x16x32_bf16 v[86:89], v[214:217], v[38:41], v[10:13]
	v_mfma_f32_16x16x32_bf16 v[10:13], v[218:221], v[34:37], v[30:33]
	v_mfma_f32_16x16x32_bf16 v[82:85], v[234:237], v[38:41], v[10:13]
	v_mfma_f32_16x16x32_bf16 v[10:13], v[210:213], v[50:53], v[70:73]
	v_mfma_f32_16x16x32_bf16 v[70:73], v[214:217], v[54:57], v[10:13]
	v_mfma_f32_16x16x32_bf16 v[10:13], v[218:221], v[50:53], v[66:69]
	v_mfma_f32_16x16x32_bf16 v[66:69], v[234:237], v[54:57], v[10:13]
	v_mfma_f32_16x16x32_bf16 v[10:13], v[210:213], v[186:189], v[46:49]
	v_mfma_f32_16x16x32_bf16 v[46:49], v[214:217], v[190:193], v[10:13]
	v_mfma_f32_16x16x32_bf16 v[10:13], v[218:221], v[186:189], v[42:45]
	v_mfma_f32_16x16x32_bf16 v[6:9], v[210:213], v[194:197], v[6:9]
	v_mfma_f32_16x16x32_bf16 v[2:5], v[218:221], v[194:197], v[2:5]
	v_mfma_f32_16x16x32_bf16 v[42:45], v[234:237], v[190:193], v[10:13]
	v_mfma_f32_16x16x32_bf16 v[6:9], v[214:217], v[198:201], v[6:9]
	v_mfma_f32_16x16x32_bf16 v[2:5], v[234:237], v[198:201], v[2:5]
	s_setprio 0
	s_add_i32 vcc_lo, vcc_lo, 2
	s_add_u32 s34, s34, 0x100
	s_addc_u32 s35, s35, 0
	s_add_u32 s56, s56, 0x100
	s_addc_u32 s57, s57, 0
	s_cmp_gt_u32 vcc_lo, 13
	s_barrier

.LBB0_2844:
	s_ashr_i32 s37, s36, 31
	v_cmp_lt_i64_e32 vcc, s[18:19], v[192:193]
	s_lshl_b64 s[18:19], s[36:37], 19
	s_add_u32 s38, s48, s18
	s_addc_u32 s39, s49, s19
	s_and_b64 s[18:19], vcc, exec
	s_cselect_b32 s37, s39, s45
	s_cselect_b32 s43, s38, s44
	s_ashr_i32 s35, s34, 31
	s_lshl_b64 s[18:19], s[34:35], 19
	s_add_u32 s40, s50, s18
	s_addc_u32 s41, s51, s19
	s_and_b64 s[18:19], vcc, exec
	s_cselect_b32 s35, s41, s47
	s_cselect_b32 s70, s40, s46
	s_add_u32 s44, s44, 0x40080
	s_addc_u32 s45, s45, 0
	s_add_u32 s71, s46, 0x100
	s_addc_u32 s72, s47, 0
	s_mov_b32 s73, -2
	s_waitcnt lgkmcnt(0)
	s_waitcnt vmcnt(0)
	ds_read_b128 v[98:101], v173
	ds_read_b128 v[102:105], v173 offset:1024
	ds_read_b128 v[106:109], v173 offset:2048
	ds_read_b128 v[110:113], v173 offset:3072
	s_add_u32 s18, s44, 0xfffc0080
	s_addc_u32 s19, s45, -1
	s_cmp_eq_u32 s73, 12
	s_cselect_b32 s19, s37, s19
	s_cselect_b32 s18, s43, s18
	s_cselect_b32 s47, s35, s72
	s_cselect_b32 s46, s70, s71
	v_lshl_add_u64 v[204:205], s[44:45], 0, v[188:189]
	s_add_i32 m0, s53, 0xc000
	ds_read_b128 v[146:149], v185
	ds_read_b128 v[150:153], v185 offset:1024
	ds_read_b128 v[154:157], v185 offset:2048
	ds_read_b128 v[158:161], v185 offset:3072
	ds_read_b128 v[162:165], v185 offset:4096
	ds_read_b128 v[166:169], v185 offset:5120
	ds_read_b128 v[196:199], v185 offset:6144
	ds_read_b128 v[200:203], v185 offset:7168
	global_load_lds_dwordx4 v[204:205], off
	v_lshl_add_u64 v[204:205], s[44:45], 0, v[190:191]
	s_add_i32 m0, s53, 0xe000
	s_nop 0
	global_load_lds_dwordx4 v[204:205], off
	s_waitcnt lgkmcnt(8)
	s_barrier
	s_waitcnt lgkmcnt(0)
	s_setprio 1
	s_waitcnt lgkmcnt(0)
	v_mfma_f32_16x16x32_bf16 v[142:145], v[98:101], v[146:149], 0
	v_mfma_f32_16x16x32_bf16 v[138:141], v[106:109], v[146:149], 0
	v_mfma_f32_16x16x32_bf16 v[126:129], v[98:101], v[154:157], 0
	v_mfma_f32_16x16x32_bf16 v[122:125], v[106:109], v[154:157], 0
	v_mfma_f32_16x16x32_bf16 v[94:97], v[98:101], v[162:165], 0
	v_mfma_f32_16x16x32_bf16 v[90:93], v[106:109], v[162:165], 0
	v_mfma_f32_16x16x32_bf16 v[78:81], v[98:101], v[196:199], 0
	v_mfma_f32_16x16x32_bf16 v[74:77], v[106:109], v[196:199], 0
	v_mfma_f32_16x16x32_bf16 v[142:145], v[102:105], v[150:153], v[142:145]
	v_mfma_f32_16x16x32_bf16 v[138:141], v[110:113], v[150:153], v[138:141]
	v_mfma_f32_16x16x32_bf16 v[126:129], v[102:105], v[158:161], v[126:129]
	v_mfma_f32_16x16x32_bf16 v[122:125], v[110:113], v[158:161], v[122:125]
	v_mfma_f32_16x16x32_bf16 v[94:97], v[102:105], v[166:169], v[94:97]
	v_mfma_f32_16x16x32_bf16 v[90:93], v[110:113], v[166:169], v[90:93]
	v_mfma_f32_16x16x32_bf16 v[78:81], v[102:105], v[200:203], v[78:81]
	v_mfma_f32_16x16x32_bf16 v[74:77], v[110:113], v[200:203], v[74:77]
	s_setprio 0
	s_barrier
	s_add_i32 s20, s65, s52
	v_lshl_add_u64 v[220:221], s[46:47], 0, v[176:177]
	s_mov_b32 m0, s20
	ds_read_b128 v[204:207], v222
	ds_read_b128 v[208:211], v222 offset:1024
	ds_read_b128 v[212:215], v222 offset:2048
	ds_read_b128 v[216:219], v222 offset:3072
	global_load_lds_dwordx4 v[220:221], off
	v_lshl_add_u64 v[224:225], s[46:47], 0, v[180:181]
	s_add_i32 m0, s20, 0x2000
	s_nop 0
	global_load_lds_dwordx4 v[224:225], off
	s_barrier
	s_waitcnt lgkmcnt(0)
	s_setprio 1
	s_waitcnt lgkmcnt(0)
	v_mfma_f32_16x16x32_bf16 v[134:137], v[204:207], v[146:149], 0
	v_mfma_f32_16x16x32_bf16 v[130:133], v[212:215], v[146:149], 0
	v_mfma_f32_16x16x32_bf16 v[118:121], v[204:207], v[154:157], 0
	v_mfma_f32_16x16x32_bf16 v[114:117], v[212:215], v[154:157], 0
	v_mfma_f32_16x16x32_bf16 v[86:89], v[204:207], v[162:165], 0
	v_mfma_f32_16x16x32_bf16 v[82:85], v[212:215], v[162:165], 0
	v_mfma_f32_16x16x32_bf16 v[70:73], v[204:207], v[196:199], 0
	v_mfma_f32_16x16x32_bf16 v[66:69], v[212:215], v[196:199], 0
	v_mfma_f32_16x16x32_bf16 v[134:137], v[208:211], v[150:153], v[134:137]
	v_mfma_f32_16x16x32_bf16 v[130:133], v[216:219], v[150:153], v[130:133]
	v_mfma_f32_16x16x32_bf16 v[118:121], v[208:211], v[158:161], v[118:121]
	v_mfma_f32_16x16x32_bf16 v[114:117], v[216:219], v[158:161], v[114:117]
	v_mfma_f32_16x16x32_bf16 v[86:89], v[208:211], v[166:169], v[86:89]
	v_mfma_f32_16x16x32_bf16 v[82:85], v[216:219], v[166:169], v[82:85]
	v_mfma_f32_16x16x32_bf16 v[70:73], v[208:211], v[200:203], v[70:73]
	v_mfma_f32_16x16x32_bf16 v[66:69], v[216:219], v[200:203], v[66:69]
	s_setprio 0
	s_mov_b32 m0, s53
	v_lshl_add_u64 v[226:227], s[18:19], 0, v[174:175]
	s_barrier
	ds_read_b128 v[146:149], v185 offset:16384
	ds_read_b128 v[150:153], v185 offset:17408
	ds_read_b128 v[154:157], v185 offset:18432
	ds_read_b128 v[158:161], v185 offset:19456
	ds_read_b128 v[162:165], v185 offset:20480
	ds_read_b128 v[166:169], v185 offset:21504
	ds_read_b128 v[196:199], v185 offset:22528
	ds_read_b128 v[200:203], v185 offset:23552
	global_load_lds_dwordx4 v[226:227], off
	v_lshl_add_u64 v[228:229], s[18:19], 0, v[178:179]
	s_mov_b32 m0, s54
	s_nop 0
	global_load_lds_dwordx4 v[228:229], off
	s_barrier
	s_waitcnt lgkmcnt(0)
	s_setprio 1
	s_waitcnt lgkmcnt(0)
	v_mfma_f32_16x16x32_bf16 v[62:65], v[98:101], v[146:149], 0
	v_mfma_f32_16x16x32_bf16 v[58:61], v[106:109], v[146:149], 0
	v_mfma_f32_16x16x32_bf16 v[46:49], v[98:101], v[154:157], 0
	v_mfma_f32_16x16x32_bf16 v[42:45], v[106:109], v[154:157], 0
	v_mfma_f32_16x16x32_bf16 v[30:33], v[98:101], v[162:165], 0
	v_mfma_f32_16x16x32_bf16 v[26:29], v[106:109], v[162:165], 0
	v_mfma_f32_16x16x32_bf16 v[14:17], v[98:101], v[196:199], 0
	v_mfma_f32_16x16x32_bf16 v[10:13], v[106:109], v[196:199], 0
	v_mfma_f32_16x16x32_bf16 v[62:65], v[102:105], v[150:153], v[62:65]
	v_mfma_f32_16x16x32_bf16 v[58:61], v[110:113], v[150:153], v[58:61]
	v_mfma_f32_16x16x32_bf16 v[46:49], v[102:105], v[158:161], v[46:49]
	v_mfma_f32_16x16x32_bf16 v[42:45], v[110:113], v[158:161], v[42:45]
	v_mfma_f32_16x16x32_bf16 v[30:33], v[102:105], v[166:169], v[30:33]
	v_mfma_f32_16x16x32_bf16 v[26:29], v[110:113], v[166:169], v[26:29]
	v_mfma_f32_16x16x32_bf16 v[14:17], v[102:105], v[200:203], v[14:17]
	v_mfma_f32_16x16x32_bf16 v[10:13], v[110:113], v[200:203], v[10:13]
	s_setprio 0
	s_barrier
	s_add_u32 s20, s46, 0x40000
	s_addc_u32 s21, s47, 0
	s_add_i32 s74, s66, s52
	v_lshl_add_u64 v[98:99], s[20:21], 0, v[176:177]
	s_mov_b32 m0, s74
	s_nop 0
	global_load_lds_dwordx4 v[98:99], off
	v_lshl_add_u64 v[98:99], s[20:21], 0, v[180:181]
	s_add_i32 m0, s74, 0x2000
	s_nop 0
	global_load_lds_dwordx4 v[98:99], off
	s_waitcnt vmcnt(6)
	s_barrier
	s_setprio 1
	v_mfma_f32_16x16x32_bf16 v[54:57], v[204:207], v[146:149], 0
	v_mfma_f32_16x16x32_bf16 v[50:53], v[212:215], v[146:149], 0
	v_mfma_f32_16x16x32_bf16 v[38:41], v[204:207], v[154:157], 0
	v_mfma_f32_16x16x32_bf16 v[34:37], v[212:215], v[154:157], 0
	v_mfma_f32_16x16x32_bf16 v[22:25], v[204:207], v[162:165], 0
	v_mfma_f32_16x16x32_bf16 v[18:21], v[212:215], v[162:165], 0
	v_mfma_f32_16x16x32_bf16 v[6:9], v[204:207], v[196:199], 0
	v_mfma_f32_16x16x32_bf16 v[2:5], v[212:215], v[196:199], 0
	v_mfma_f32_16x16x32_bf16 v[54:57], v[208:211], v[150:153], v[54:57]
	v_mfma_f32_16x16x32_bf16 v[50:53], v[216:219], v[150:153], v[50:53]
	v_mfma_f32_16x16x32_bf16 v[38:41], v[208:211], v[158:161], v[38:41]
	v_mfma_f32_16x16x32_bf16 v[34:37], v[216:219], v[158:161], v[34:37]
	v_mfma_f32_16x16x32_bf16 v[22:25], v[208:211], v[166:169], v[22:25]
	v_mfma_f32_16x16x32_bf16 v[18:21], v[216:219], v[166:169], v[18:21]
	v_mfma_f32_16x16x32_bf16 v[6:9], v[208:211], v[200:203], v[6:9]
	v_mfma_f32_16x16x32_bf16 v[2:5], v[216:219], v[200:203], v[2:5]
	s_setprio 0
	s_add_i32 s20, 0, 0x18000
	v_add_u32_e32 v110, s20, v171
	s_barrier
	ds_read_b128 v[98:101], v110
	ds_read_b128 v[102:105], v110 offset:1024
	ds_read_b128 v[106:109], v110 offset:2048
	ds_read_b128 v[110:113], v110 offset:3072
	s_add_u32 s18, s18, 0x40000
	s_addc_u32 s19, s19, 0
	s_mov_b32 m0, s55
	v_lshl_add_u64 v[204:205], s[18:19], 0, v[174:175]
	ds_read_b128 v[146:149], v185 offset:32768
	ds_read_b128 v[150:153], v185 offset:33792
	ds_read_b128 v[154:157], v185 offset:34816
	ds_read_b128 v[158:161], v185 offset:35840
	ds_read_b128 v[162:165], v185 offset:36864
	ds_read_b128 v[166:169], v185 offset:37888
	ds_read_b128 v[196:199], v185 offset:38912
	ds_read_b128 v[200:203], v185 offset:39936
	global_load_lds_dwordx4 v[204:205], off
	v_lshl_add_u64 v[204:205], s[18:19], 0, v[178:179]
	s_mov_b32 m0, s56
	s_nop 0
	global_load_lds_dwordx4 v[204:205], off
	s_waitcnt lgkmcnt(8)
	s_barrier
	s_waitcnt lgkmcnt(0)
	s_setprio 1
	s_waitcnt lgkmcnt(0)
	v_mfma_f32_16x16x32_bf16 v[142:145], v[98:101], v[146:149], v[142:145]
	v_mfma_f32_16x16x32_bf16 v[138:141], v[106:109], v[146:149], v[138:141]
	v_mfma_f32_16x16x32_bf16 v[126:129], v[98:101], v[154:157], v[126:129]
	v_mfma_f32_16x16x32_bf16 v[122:125], v[106:109], v[154:157], v[122:125]
	v_mfma_f32_16x16x32_bf16 v[94:97], v[98:101], v[162:165], v[94:97]
	v_mfma_f32_16x16x32_bf16 v[90:93], v[106:109], v[162:165], v[90:93]
	v_mfma_f32_16x16x32_bf16 v[78:81], v[98:101], v[196:199], v[78:81]
	v_mfma_f32_16x16x32_bf16 v[74:77], v[106:109], v[196:199], v[74:77]
	v_mfma_f32_16x16x32_bf16 v[142:145], v[102:105], v[150:153], v[142:145]
	v_mfma_f32_16x16x32_bf16 v[138:141], v[110:113], v[150:153], v[138:141]
	v_mfma_f32_16x16x32_bf16 v[126:129], v[102:105], v[158:161], v[126:129]
	v_mfma_f32_16x16x32_bf16 v[122:125], v[110:113], v[158:161], v[122:125]
	v_mfma_f32_16x16x32_bf16 v[94:97], v[102:105], v[166:169], v[94:97]
	v_mfma_f32_16x16x32_bf16 v[90:93], v[110:113], v[166:169], v[90:93]
	v_mfma_f32_16x16x32_bf16 v[78:81], v[102:105], v[200:203], v[78:81]
	v_mfma_f32_16x16x32_bf16 v[74:77], v[110:113], v[200:203], v[74:77]
	s_setprio 0
	s_barrier
	s_add_i32 s21, 0, 0x1c000
	s_add_i32 s18, s20, s52
	v_add_u32_e32 v182, s21, v171
	v_lshl_add_u64 v[220:221], v[220:221], 0, s[10:11]
	s_mov_b32 m0, s18
	ds_read_b128 v[204:207], v182
	ds_read_b128 v[208:211], v182 offset:1024
	ds_read_b128 v[212:215], v182 offset:2048
	ds_read_b128 v[216:219], v182 offset:3072
	global_load_lds_dwordx4 v[220:221], off
	v_lshl_add_u64 v[220:221], v[224:225], 0, s[10:11]
	s_add_i32 m0, s18, 0x2000
	s_nop 0
	global_load_lds_dwordx4 v[220:221], off
	s_barrier
	s_waitcnt lgkmcnt(0)
	s_setprio 1
	s_waitcnt lgkmcnt(0)
	v_mfma_f32_16x16x32_bf16 v[134:137], v[204:207], v[146:149], v[134:137]
	v_mfma_f32_16x16x32_bf16 v[130:133], v[212:215], v[146:149], v[130:133]
	v_mfma_f32_16x16x32_bf16 v[118:121], v[204:207], v[154:157], v[118:121]
	v_mfma_f32_16x16x32_bf16 v[114:117], v[212:215], v[154:157], v[114:117]
	v_mfma_f32_16x16x32_bf16 v[86:89], v[204:207], v[162:165], v[86:89]
	v_mfma_f32_16x16x32_bf16 v[82:85], v[212:215], v[162:165], v[82:85]
	v_mfma_f32_16x16x32_bf16 v[70:73], v[204:207], v[196:199], v[70:73]
	v_mfma_f32_16x16x32_bf16 v[66:69], v[212:215], v[196:199], v[66:69]
	v_mfma_f32_16x16x32_bf16 v[134:137], v[208:211], v[150:153], v[134:137]
	v_mfma_f32_16x16x32_bf16 v[130:133], v[216:219], v[150:153], v[130:133]
	v_mfma_f32_16x16x32_bf16 v[118:121], v[208:211], v[158:161], v[118:121]
	v_mfma_f32_16x16x32_bf16 v[114:117], v[216:219], v[158:161], v[114:117]
	v_mfma_f32_16x16x32_bf16 v[86:89], v[208:211], v[166:169], v[86:89]
	v_mfma_f32_16x16x32_bf16 v[82:85], v[216:219], v[166:169], v[82:85]
	v_mfma_f32_16x16x32_bf16 v[70:73], v[208:211], v[200:203], v[70:73]
	v_mfma_f32_16x16x32_bf16 v[66:69], v[216:219], v[200:203], v[66:69]
	s_setprio 0
	s_mov_b32 m0, s62
	v_lshl_add_u64 v[220:221], v[226:227], 0, s[10:11]
	s_barrier
	ds_read_b128 v[146:149], v185 offset:49152
	ds_read_b128 v[150:153], v185 offset:50176
	ds_read_b128 v[154:157], v185 offset:51200
	ds_read_b128 v[158:161], v185 offset:52224
	ds_read_b128 v[162:165], v185 offset:53248
	ds_read_b128 v[166:169], v185 offset:54272
	ds_read_b128 v[196:199], v185 offset:55296
	ds_read_b128 v[200:203], v185 offset:56320
	global_load_lds_dwordx4 v[220:221], off
	v_lshl_add_u64 v[220:221], v[228:229], 0, s[10:11]
	s_mov_b32 m0, s63
	s_nop 0
	global_load_lds_dwordx4 v[220:221], off
	s_barrier
	s_waitcnt lgkmcnt(0)
	s_setprio 1
	s_waitcnt lgkmcnt(0)
	v_mfma_f32_16x16x32_bf16 v[62:65], v[98:101], v[146:149], v[62:65]
	v_mfma_f32_16x16x32_bf16 v[58:61], v[106:109], v[146:149], v[58:61]
	v_mfma_f32_16x16x32_bf16 v[46:49], v[98:101], v[154:157], v[46:49]
	v_mfma_f32_16x16x32_bf16 v[42:45], v[106:109], v[154:157], v[42:45]
	v_mfma_f32_16x16x32_bf16 v[30:33], v[98:101], v[162:165], v[30:33]
	v_mfma_f32_16x16x32_bf16 v[26:29], v[106:109], v[162:165], v[26:29]
	v_mfma_f32_16x16x32_bf16 v[14:17], v[98:101], v[196:199], v[14:17]
	v_mfma_f32_16x16x32_bf16 v[10:13], v[106:109], v[196:199], v[10:13]
	v_mfma_f32_16x16x32_bf16 v[62:65], v[102:105], v[150:153], v[62:65]
	v_mfma_f32_16x16x32_bf16 v[58:61], v[110:113], v[150:153], v[58:61]
	v_mfma_f32_16x16x32_bf16 v[46:49], v[102:105], v[158:161], v[46:49]
	v_mfma_f32_16x16x32_bf16 v[42:45], v[110:113], v[158:161], v[42:45]
	v_mfma_f32_16x16x32_bf16 v[30:33], v[102:105], v[166:169], v[30:33]
	v_mfma_f32_16x16x32_bf16 v[26:29], v[110:113], v[166:169], v[26:29]
	v_mfma_f32_16x16x32_bf16 v[14:17], v[102:105], v[200:203], v[14:17]
	v_mfma_f32_16x16x32_bf16 v[10:13], v[110:113], v[200:203], v[10:13]
	s_setprio 0
	s_barrier
	s_add_u32 s18, s46, 0x40080
	s_addc_u32 s19, s47, 0
	s_add_i32 s20, s21, s52
	v_lshl_add_u64 v[98:99], s[18:19], 0, v[176:177]
	s_mov_b32 m0, s20
	s_nop 0
	global_load_lds_dwordx4 v[98:99], off
	v_lshl_add_u64 v[98:99], s[18:19], 0, v[180:181]
	s_add_i32 m0, s20, 0x2000
	s_nop 0
	global_load_lds_dwordx4 v[98:99], off
	s_waitcnt vmcnt(6)
	s_barrier
	s_setprio 1
	v_mfma_f32_16x16x32_bf16 v[54:57], v[204:207], v[146:149], v[54:57]
	v_mfma_f32_16x16x32_bf16 v[50:53], v[212:215], v[146:149], v[50:53]
	v_mfma_f32_16x16x32_bf16 v[38:41], v[204:207], v[154:157], v[38:41]
	v_mfma_f32_16x16x32_bf16 v[34:37], v[212:215], v[154:157], v[34:37]
	v_mfma_f32_16x16x32_bf16 v[22:25], v[204:207], v[162:165], v[22:25]
	v_mfma_f32_16x16x32_bf16 v[18:21], v[212:215], v[162:165], v[18:21]
	v_mfma_f32_16x16x32_bf16 v[6:9], v[204:207], v[196:199], v[6:9]
	v_mfma_f32_16x16x32_bf16 v[2:5], v[212:215], v[196:199], v[2:5]
	v_mfma_f32_16x16x32_bf16 v[54:57], v[208:211], v[150:153], v[54:57]
	v_mfma_f32_16x16x32_bf16 v[50:53], v[216:219], v[150:153], v[50:53]
	v_mfma_f32_16x16x32_bf16 v[38:41], v[208:211], v[158:161], v[38:41]
	v_mfma_f32_16x16x32_bf16 v[34:37], v[216:219], v[158:161], v[34:37]
	v_mfma_f32_16x16x32_bf16 v[22:25], v[208:211], v[166:169], v[22:25]
	v_mfma_f32_16x16x32_bf16 v[18:21], v[216:219], v[166:169], v[18:21]
	v_mfma_f32_16x16x32_bf16 v[6:9], v[208:211], v[200:203], v[6:9]
	v_mfma_f32_16x16x32_bf16 v[2:5], v[216:219], v[200:203], v[2:5]
	s_setprio 0
	s_add_i32 s73, s73, 2
	s_add_u32 s44, s44, 0x100
	s_addc_u32 s45, s45, 0
	s_add_u32 s71, s71, 0x100
	s_addc_u32 s72, s72, 0
	s_cmp_gt_u32 s73, 13
	s_barrier

.LBB0_3264:
	s_ashr_i32 s11, s10, 31
	v_cmp_lt_i64_e32 vcc, s[12:13], v[162:163]
	s_lshl_b64 s[12:13], s[10:11], 19
	s_add_u32 s12, s36, s12
	s_addc_u32 s13, s37, s13
	s_and_b64 s[14:15], vcc, exec
	s_cselect_b32 s11, s13, s25
	s_cselect_b32 s57, s12, s24
	s_ashr_i32 s9, s8, 31
	s_lshl_b64 s[14:15], s[8:9], 19
	s_add_u32 s14, s38, s14
	s_addc_u32 s15, s39, s15
	s_and_b64 s[18:19], vcc, exec
	s_cselect_b32 s9, s15, s35
	s_cselect_b32 s60, s14, s34
	s_add_u32 s24, s24, 0x40080
	s_addc_u32 s25, s25, 0
	s_add_u32 s61, s34, 0x100
	s_addc_u32 s62, s35, 0
	s_mov_b32 s63, -2
	ds_read_b128 v[130:133], v171
	ds_read_b128 v[134:137], v171 offset:1024
	ds_read_b128 v[138:141], v171 offset:2048
	ds_read_b128 v[142:145], v171 offset:3072
	s_add_u32 s18, s24, 0xfffc0080
	s_addc_u32 s19, s25, -1
	s_cmp_eq_u32 s63, 12
	s_cselect_b32 s19, s11, s19
	s_cselect_b32 s18, s57, s18
	s_cselect_b32 s35, s9, s62
	s_cselect_b32 s34, s60, s61
	v_lshl_add_u64 v[174:175], s[24:25], 0, v[158:159]
	s_add_i32 m0, s43, 0xc000
	ds_read_b128 v[166:169], v173
	ds_read_b128 v[178:181], v173 offset:1024
	ds_read_b128 v[182:185], v173 offset:2048
	ds_read_b128 v[186:189], v173 offset:3072
	ds_read_b128 v[190:193], v173 offset:4096
	ds_read_b128 v[194:197], v173 offset:5120
	ds_read_b128 v[198:201], v173 offset:6144
	ds_read_b128 v[202:205], v173 offset:7168
	global_load_lds_dwordx4 v[174:175], off
	v_lshl_add_u64 v[174:175], s[24:25], 0, v[160:161]
	s_add_i32 m0, s43, 0xe000
	s_nop 0
	global_load_lds_dwordx4 v[174:175], off
	s_waitcnt lgkmcnt(8)
	s_barrier
	s_waitcnt lgkmcnt(0)
	s_setprio 1
	s_waitcnt lgkmcnt(0)
	v_mfma_f32_16x16x32_bf16 v[126:129], v[130:133], v[166:169], 0
	v_mfma_f32_16x16x32_bf16 v[122:125], v[138:141], v[166:169], 0
	v_mfma_f32_16x16x32_bf16 v[110:113], v[130:133], v[182:185], 0
	v_mfma_f32_16x16x32_bf16 v[106:109], v[138:141], v[182:185], 0
	v_mfma_f32_16x16x32_bf16 v[94:97], v[130:133], v[190:193], 0
	v_mfma_f32_16x16x32_bf16 v[90:93], v[138:141], v[190:193], 0
	v_mfma_f32_16x16x32_bf16 v[78:81], v[130:133], v[198:201], 0
	v_mfma_f32_16x16x32_bf16 v[74:77], v[138:141], v[198:201], 0
	v_mfma_f32_16x16x32_bf16 v[126:129], v[134:137], v[178:181], v[126:129]
	v_mfma_f32_16x16x32_bf16 v[122:125], v[142:145], v[178:181], v[122:125]
	v_mfma_f32_16x16x32_bf16 v[110:113], v[134:137], v[186:189], v[110:113]
	v_mfma_f32_16x16x32_bf16 v[106:109], v[142:145], v[186:189], v[106:109]
	v_mfma_f32_16x16x32_bf16 v[94:97], v[134:137], v[194:197], v[94:97]
	v_mfma_f32_16x16x32_bf16 v[90:93], v[142:145], v[194:197], v[90:93]
	v_mfma_f32_16x16x32_bf16 v[78:81], v[134:137], v[202:205], v[78:81]
	v_mfma_f32_16x16x32_bf16 v[74:77], v[142:145], v[202:205], v[74:77]
	s_setprio 0
	s_barrier
	s_add_i32 s20, s54, s42
	v_lshl_add_u64 v[174:175], s[34:35], 0, v[150:151]
	s_mov_b32 m0, s20
	ds_read_b128 v[206:209], v177
	ds_read_b128 v[210:213], v177 offset:1024
	ds_read_b128 v[214:217], v177 offset:2048
	ds_read_b128 v[218:221], v177 offset:3072
	global_load_lds_dwordx4 v[174:175], off
	v_lshl_add_u64 v[222:223], s[34:35], 0, v[146:147]
	s_add_i32 m0, s20, 0x2000
	s_nop 0
	global_load_lds_dwordx4 v[222:223], off
	s_barrier
	s_waitcnt lgkmcnt(0)
	s_setprio 1
	s_waitcnt lgkmcnt(0)
	v_mfma_f32_16x16x32_bf16 v[118:121], v[206:209], v[166:169], 0
	v_mfma_f32_16x16x32_bf16 v[114:117], v[214:217], v[166:169], 0
	v_mfma_f32_16x16x32_bf16 v[102:105], v[206:209], v[182:185], 0
	v_mfma_f32_16x16x32_bf16 v[98:101], v[214:217], v[182:185], 0
	v_mfma_f32_16x16x32_bf16 v[86:89], v[206:209], v[190:193], 0
	v_mfma_f32_16x16x32_bf16 v[82:85], v[214:217], v[190:193], 0
	v_mfma_f32_16x16x32_bf16 v[70:73], v[206:209], v[198:201], 0
	v_mfma_f32_16x16x32_bf16 v[66:69], v[214:217], v[198:201], 0
	v_mfma_f32_16x16x32_bf16 v[118:121], v[210:213], v[178:181], v[118:121]
	v_mfma_f32_16x16x32_bf16 v[114:117], v[218:221], v[178:181], v[114:117]
	v_mfma_f32_16x16x32_bf16 v[102:105], v[210:213], v[186:189], v[102:105]
	v_mfma_f32_16x16x32_bf16 v[98:101], v[218:221], v[186:189], v[98:101]
	v_mfma_f32_16x16x32_bf16 v[86:89], v[210:213], v[194:197], v[86:89]
	v_mfma_f32_16x16x32_bf16 v[82:85], v[218:221], v[194:197], v[82:85]
	v_mfma_f32_16x16x32_bf16 v[70:73], v[210:213], v[202:205], v[70:73]
	v_mfma_f32_16x16x32_bf16 v[66:69], v[218:221], v[202:205], v[66:69]
	s_setprio 0
	s_mov_b32 m0, s43
	v_lshl_add_u64 v[224:225], s[18:19], 0, v[152:153]
	s_barrier
	ds_read_b128 v[166:169], v173 offset:16384
	ds_read_b128 v[178:181], v173 offset:17408
	ds_read_b128 v[182:185], v173 offset:18432
	ds_read_b128 v[186:189], v173 offset:19456
	ds_read_b128 v[190:193], v173 offset:20480
	ds_read_b128 v[194:197], v173 offset:21504
	ds_read_b128 v[198:201], v173 offset:22528
	ds_read_b128 v[202:205], v173 offset:23552
	global_load_lds_dwordx4 v[224:225], off
	v_lshl_add_u64 v[226:227], s[18:19], 0, v[148:149]
	s_mov_b32 m0, s44
	s_nop 0
	global_load_lds_dwordx4 v[226:227], off
	s_barrier
	s_waitcnt lgkmcnt(0)
	s_setprio 1
	s_waitcnt lgkmcnt(0)
	v_mfma_f32_16x16x32_bf16 v[62:65], v[130:133], v[166:169], 0
	v_mfma_f32_16x16x32_bf16 v[58:61], v[138:141], v[166:169], 0
	v_mfma_f32_16x16x32_bf16 v[46:49], v[130:133], v[182:185], 0
	v_mfma_f32_16x16x32_bf16 v[42:45], v[138:141], v[182:185], 0
	v_mfma_f32_16x16x32_bf16 v[30:33], v[130:133], v[190:193], 0
	v_mfma_f32_16x16x32_bf16 v[26:29], v[138:141], v[190:193], 0
	v_mfma_f32_16x16x32_bf16 v[14:17], v[130:133], v[198:201], 0
	v_mfma_f32_16x16x32_bf16 v[10:13], v[138:141], v[198:201], 0
	v_mfma_f32_16x16x32_bf16 v[62:65], v[134:137], v[178:181], v[62:65]
	v_mfma_f32_16x16x32_bf16 v[58:61], v[142:145], v[178:181], v[58:61]
	v_mfma_f32_16x16x32_bf16 v[46:49], v[134:137], v[186:189], v[46:49]
	v_mfma_f32_16x16x32_bf16 v[42:45], v[142:145], v[186:189], v[42:45]
	v_mfma_f32_16x16x32_bf16 v[30:33], v[134:137], v[194:197], v[30:33]
	v_mfma_f32_16x16x32_bf16 v[26:29], v[142:145], v[194:197], v[26:29]
	v_mfma_f32_16x16x32_bf16 v[14:17], v[134:137], v[202:205], v[14:17]
	v_mfma_f32_16x16x32_bf16 v[10:13], v[142:145], v[202:205], v[10:13]
	s_setprio 0
	s_barrier
	s_add_u32 s20, s34, 0x40000
	s_addc_u32 s21, s35, 0
	s_add_i32 s64, s55, s42
	v_lshl_add_u64 v[130:131], s[20:21], 0, v[150:151]
	s_mov_b32 m0, s64
	s_nop 0
	global_load_lds_dwordx4 v[130:131], off
	v_lshl_add_u64 v[130:131], s[20:21], 0, v[146:147]
	s_add_i32 m0, s64, 0x2000
	s_nop 0
	global_load_lds_dwordx4 v[130:131], off
	s_waitcnt vmcnt(6)
	s_barrier
	s_setprio 1
	v_mfma_f32_16x16x32_bf16 v[54:57], v[206:209], v[166:169], 0
	v_mfma_f32_16x16x32_bf16 v[50:53], v[214:217], v[166:169], 0
	v_mfma_f32_16x16x32_bf16 v[38:41], v[206:209], v[182:185], 0
	v_mfma_f32_16x16x32_bf16 v[34:37], v[214:217], v[182:185], 0
	v_mfma_f32_16x16x32_bf16 v[22:25], v[206:209], v[190:193], 0
	v_mfma_f32_16x16x32_bf16 v[18:21], v[214:217], v[190:193], 0
	v_mfma_f32_16x16x32_bf16 v[6:9], v[206:209], v[198:201], 0
	v_mfma_f32_16x16x32_bf16 v[2:5], v[214:217], v[198:201], 0
	v_mfma_f32_16x16x32_bf16 v[54:57], v[210:213], v[178:181], v[54:57]
	v_mfma_f32_16x16x32_bf16 v[50:53], v[218:221], v[178:181], v[50:53]
	v_mfma_f32_16x16x32_bf16 v[38:41], v[210:213], v[186:189], v[38:41]
	v_mfma_f32_16x16x32_bf16 v[34:37], v[218:221], v[186:189], v[34:37]
	v_mfma_f32_16x16x32_bf16 v[22:25], v[210:213], v[194:197], v[22:25]
	v_mfma_f32_16x16x32_bf16 v[18:21], v[218:221], v[194:197], v[18:21]
	v_mfma_f32_16x16x32_bf16 v[6:9], v[210:213], v[202:205], v[6:9]
	v_mfma_f32_16x16x32_bf16 v[2:5], v[218:221], v[202:205], v[2:5]
	s_setprio 0
	s_add_i32 s20, 0, 0x18000
	v_add_u32_e32 v142, s20, v157
	s_barrier
	ds_read_b128 v[130:133], v142
	ds_read_b128 v[134:137], v142 offset:1024
	ds_read_b128 v[138:141], v142 offset:2048
	ds_read_b128 v[142:145], v142 offset:3072
	s_add_u32 s18, s18, 0x40000
	s_addc_u32 s19, s19, 0
	s_mov_b32 m0, s45
	v_lshl_add_u64 v[206:207], s[18:19], 0, v[152:153]
	ds_read_b128 v[166:169], v173 offset:32768
	ds_read_b128 v[178:181], v173 offset:33792
	ds_read_b128 v[182:185], v173 offset:34816
	ds_read_b128 v[186:189], v173 offset:35840
	ds_read_b128 v[190:193], v173 offset:36864
	ds_read_b128 v[194:197], v173 offset:37888
	ds_read_b128 v[198:201], v173 offset:38912
	ds_read_b128 v[202:205], v173 offset:39936
	global_load_lds_dwordx4 v[206:207], off
	v_lshl_add_u64 v[206:207], s[18:19], 0, v[148:149]
	s_mov_b32 m0, s46
	s_nop 0
	global_load_lds_dwordx4 v[206:207], off
	s_waitcnt lgkmcnt(8)
	s_barrier
	s_waitcnt lgkmcnt(0)
	s_setprio 1
	s_waitcnt lgkmcnt(0)
	v_mfma_f32_16x16x32_bf16 v[126:129], v[130:133], v[166:169], v[126:129]
	v_mfma_f32_16x16x32_bf16 v[122:125], v[138:141], v[166:169], v[122:125]
	v_mfma_f32_16x16x32_bf16 v[110:113], v[130:133], v[182:185], v[110:113]
	v_mfma_f32_16x16x32_bf16 v[106:109], v[138:141], v[182:185], v[106:109]
	v_mfma_f32_16x16x32_bf16 v[94:97], v[130:133], v[190:193], v[94:97]
	v_mfma_f32_16x16x32_bf16 v[90:93], v[138:141], v[190:193], v[90:93]
	v_mfma_f32_16x16x32_bf16 v[78:81], v[130:133], v[198:201], v[78:81]
	v_mfma_f32_16x16x32_bf16 v[74:77], v[138:141], v[198:201], v[74:77]
	v_mfma_f32_16x16x32_bf16 v[126:129], v[134:137], v[178:181], v[126:129]
	v_mfma_f32_16x16x32_bf16 v[122:125], v[142:145], v[178:181], v[122:125]
	v_mfma_f32_16x16x32_bf16 v[110:113], v[134:137], v[186:189], v[110:113]
	v_mfma_f32_16x16x32_bf16 v[106:109], v[142:145], v[186:189], v[106:109]
	v_mfma_f32_16x16x32_bf16 v[94:97], v[134:137], v[194:197], v[94:97]
	v_mfma_f32_16x16x32_bf16 v[90:93], v[142:145], v[194:197], v[90:93]
	v_mfma_f32_16x16x32_bf16 v[78:81], v[134:137], v[202:205], v[78:81]
	v_mfma_f32_16x16x32_bf16 v[74:77], v[142:145], v[202:205], v[74:77]
	s_setprio 0
	s_barrier
	s_add_i32 s21, 0, 0x1c000
	s_add_i32 s18, s20, s42
	v_add_u32_e32 v154, s21, v157
	v_lshl_add_u64 v[174:175], v[174:175], 0, s[6:7]
	s_mov_b32 m0, s18
	ds_read_b128 v[206:209], v154
	ds_read_b128 v[210:213], v154 offset:1024
	ds_read_b128 v[214:217], v154 offset:2048
	ds_read_b128 v[218:221], v154 offset:3072
	global_load_lds_dwordx4 v[174:175], off
	v_lshl_add_u64 v[174:175], v[222:223], 0, s[6:7]
	s_add_i32 m0, s18, 0x2000
	s_nop 0
	global_load_lds_dwordx4 v[174:175], off
	s_barrier
	s_waitcnt lgkmcnt(0)
	s_setprio 1
	s_waitcnt lgkmcnt(0)
	v_mfma_f32_16x16x32_bf16 v[118:121], v[206:209], v[166:169], v[118:121]
	v_mfma_f32_16x16x32_bf16 v[114:117], v[214:217], v[166:169], v[114:117]
	v_mfma_f32_16x16x32_bf16 v[102:105], v[206:209], v[182:185], v[102:105]
	v_mfma_f32_16x16x32_bf16 v[98:101], v[214:217], v[182:185], v[98:101]
	v_mfma_f32_16x16x32_bf16 v[86:89], v[206:209], v[190:193], v[86:89]
	v_mfma_f32_16x16x32_bf16 v[82:85], v[214:217], v[190:193], v[82:85]
	v_mfma_f32_16x16x32_bf16 v[70:73], v[206:209], v[198:201], v[70:73]
	v_mfma_f32_16x16x32_bf16 v[66:69], v[214:217], v[198:201], v[66:69]
	v_mfma_f32_16x16x32_bf16 v[118:121], v[210:213], v[178:181], v[118:121]
	v_mfma_f32_16x16x32_bf16 v[114:117], v[218:221], v[178:181], v[114:117]
	v_mfma_f32_16x16x32_bf16 v[102:105], v[210:213], v[186:189], v[102:105]
	v_mfma_f32_16x16x32_bf16 v[98:101], v[218:221], v[186:189], v[98:101]
	v_mfma_f32_16x16x32_bf16 v[86:89], v[210:213], v[194:197], v[86:89]
	v_mfma_f32_16x16x32_bf16 v[82:85], v[218:221], v[194:197], v[82:85]
	v_mfma_f32_16x16x32_bf16 v[70:73], v[210:213], v[202:205], v[70:73]
	v_mfma_f32_16x16x32_bf16 v[66:69], v[218:221], v[202:205], v[66:69]
	s_setprio 0
	s_mov_b32 m0, s50
	v_lshl_add_u64 v[174:175], v[224:225], 0, s[6:7]
	s_barrier
	ds_read_b128 v[166:169], v173 offset:49152
	ds_read_b128 v[178:181], v173 offset:50176
	ds_read_b128 v[182:185], v173 offset:51200
	ds_read_b128 v[186:189], v173 offset:52224
	ds_read_b128 v[190:193], v173 offset:53248
	ds_read_b128 v[194:197], v173 offset:54272
	ds_read_b128 v[198:201], v173 offset:55296
	ds_read_b128 v[202:205], v173 offset:56320
	global_load_lds_dwordx4 v[174:175], off
	v_lshl_add_u64 v[174:175], v[226:227], 0, s[6:7]
	s_mov_b32 m0, s51
	s_nop 0
	global_load_lds_dwordx4 v[174:175], off
	s_barrier
	s_waitcnt lgkmcnt(0)
	s_setprio 1
	s_waitcnt lgkmcnt(0)
	v_mfma_f32_16x16x32_bf16 v[62:65], v[130:133], v[166:169], v[62:65]
	v_mfma_f32_16x16x32_bf16 v[58:61], v[138:141], v[166:169], v[58:61]
	v_mfma_f32_16x16x32_bf16 v[46:49], v[130:133], v[182:185], v[46:49]
	v_mfma_f32_16x16x32_bf16 v[42:45], v[138:141], v[182:185], v[42:45]
	v_mfma_f32_16x16x32_bf16 v[30:33], v[130:133], v[190:193], v[30:33]
	v_mfma_f32_16x16x32_bf16 v[26:29], v[138:141], v[190:193], v[26:29]
	v_mfma_f32_16x16x32_bf16 v[14:17], v[130:133], v[198:201], v[14:17]
	v_mfma_f32_16x16x32_bf16 v[10:13], v[138:141], v[198:201], v[10:13]
	v_mfma_f32_16x16x32_bf16 v[62:65], v[134:137], v[178:181], v[62:65]
	v_mfma_f32_16x16x32_bf16 v[58:61], v[142:145], v[178:181], v[58:61]
	v_mfma_f32_16x16x32_bf16 v[46:49], v[134:137], v[186:189], v[46:49]
	v_mfma_f32_16x16x32_bf16 v[42:45], v[142:145], v[186:189], v[42:45]
	v_mfma_f32_16x16x32_bf16 v[30:33], v[134:137], v[194:197], v[30:33]
	v_mfma_f32_16x16x32_bf16 v[26:29], v[142:145], v[194:197], v[26:29]
	v_mfma_f32_16x16x32_bf16 v[14:17], v[134:137], v[202:205], v[14:17]
	v_mfma_f32_16x16x32_bf16 v[10:13], v[142:145], v[202:205], v[10:13]
	s_setprio 0
	s_barrier
	s_add_u32 s18, s34, 0x40080
	s_addc_u32 s19, s35, 0
	s_add_i32 s20, s21, s42
	v_lshl_add_u64 v[130:131], s[18:19], 0, v[150:151]
	s_mov_b32 m0, s20
	s_nop 0
	global_load_lds_dwordx4 v[130:131], off
	v_lshl_add_u64 v[130:131], s[18:19], 0, v[146:147]
	s_add_i32 m0, s20, 0x2000
	s_nop 0
	global_load_lds_dwordx4 v[130:131], off
	s_waitcnt vmcnt(6)
	s_barrier
	s_setprio 1
	v_mfma_f32_16x16x32_bf16 v[54:57], v[206:209], v[166:169], v[54:57]
	v_mfma_f32_16x16x32_bf16 v[50:53], v[214:217], v[166:169], v[50:53]
	v_mfma_f32_16x16x32_bf16 v[38:41], v[206:209], v[182:185], v[38:41]
	v_mfma_f32_16x16x32_bf16 v[34:37], v[214:217], v[182:185], v[34:37]
	v_mfma_f32_16x16x32_bf16 v[22:25], v[206:209], v[190:193], v[22:25]
	v_mfma_f32_16x16x32_bf16 v[18:21], v[214:217], v[190:193], v[18:21]
	v_mfma_f32_16x16x32_bf16 v[6:9], v[206:209], v[198:201], v[6:9]
	v_mfma_f32_16x16x32_bf16 v[2:5], v[214:217], v[198:201], v[2:5]
	v_mfma_f32_16x16x32_bf16 v[54:57], v[210:213], v[178:181], v[54:57]
	v_mfma_f32_16x16x32_bf16 v[50:53], v[218:221], v[178:181], v[50:53]
	v_mfma_f32_16x16x32_bf16 v[38:41], v[210:213], v[186:189], v[38:41]
	v_mfma_f32_16x16x32_bf16 v[34:37], v[218:221], v[186:189], v[34:37]
	v_mfma_f32_16x16x32_bf16 v[22:25], v[210:213], v[194:197], v[22:25]
	v_mfma_f32_16x16x32_bf16 v[18:21], v[218:221], v[194:197], v[18:21]
	v_mfma_f32_16x16x32_bf16 v[6:9], v[210:213], v[202:205], v[6:9]
	v_mfma_f32_16x16x32_bf16 v[2:5], v[218:221], v[202:205], v[2:5]
	s_setprio 0
	s_add_i32 s63, s63, 2
	s_add_u32 s24, s24, 0x100
	s_addc_u32 s25, s25, 0
	s_add_u32 s61, s61, 0x100
	s_addc_u32 s62, s62, 0
	s_cmp_gt_u32 s63, 13
	s_barrier

.LBB0_3482:
	s_add_u32 s24, s24, 0xb0080
	s_addc_u32 s25, s25, 0
	s_add_u32 s60, s34, 0x100
	s_addc_u32 s61, s35, 0
	s_mov_b32 s62, -2
	s_waitcnt lgkmcnt(0)
	s_waitcnt vmcnt(0)
	ds_read_b128 v[130:133], v171
	ds_read_b128 v[134:137], v171 offset:1024
	ds_read_b128 v[138:141], v171 offset:2048
	ds_read_b128 v[142:145], v171 offset:3072
	s_add_u32 s18, s24, 0xfff50080
	s_addc_u32 s19, s25, -1
	s_cmp_eq_u32 s62, 40
	s_cselect_b32 s19, s7, s19
	s_cselect_b32 s18, s6, s18
	s_cselect_b32 s35, s1, s61
	s_cselect_b32 s34, s0, s60
	v_lshl_add_u64 v[202:203], s[24:25], 0, v[168:169]
	s_add_i32 m0, s41, 0xc000
	ds_read_b128 v[146:149], v210
	ds_read_b128 v[150:153], v210 offset:1024
	ds_read_b128 v[178:181], v210 offset:2048
	ds_read_b128 v[182:185], v210 offset:3072
	ds_read_b128 v[186:189], v210 offset:4096
	ds_read_b128 v[190:193], v210 offset:5120
	ds_read_b128 v[194:197], v210 offset:6144
	ds_read_b128 v[198:201], v210 offset:7168
	global_load_lds_dwordx4 v[202:203], off
	v_lshl_add_u64 v[202:203], s[24:25], 0, v[172:173]
	s_add_i32 m0, s41, 0xe000
	s_nop 0
	global_load_lds_dwordx4 v[202:203], off
	s_waitcnt lgkmcnt(8)
	s_barrier
	s_waitcnt lgkmcnt(0)
	s_setprio 1
	s_waitcnt lgkmcnt(0)
	v_mfma_f32_16x16x32_bf16 v[126:129], v[130:133], v[146:149], 0
	v_mfma_f32_16x16x32_bf16 v[122:125], v[138:141], v[146:149], 0
	v_mfma_f32_16x16x32_bf16 v[110:113], v[130:133], v[178:181], 0
	v_mfma_f32_16x16x32_bf16 v[106:109], v[138:141], v[178:181], 0
	v_mfma_f32_16x16x32_bf16 v[94:97], v[130:133], v[186:189], 0
	v_mfma_f32_16x16x32_bf16 v[90:93], v[138:141], v[186:189], 0
	v_mfma_f32_16x16x32_bf16 v[78:81], v[130:133], v[194:197], 0
	v_mfma_f32_16x16x32_bf16 v[74:77], v[138:141], v[194:197], 0
	v_mfma_f32_16x16x32_bf16 v[126:129], v[134:137], v[150:153], v[126:129]
	v_mfma_f32_16x16x32_bf16 v[122:125], v[142:145], v[150:153], v[122:125]
	v_mfma_f32_16x16x32_bf16 v[110:113], v[134:137], v[182:185], v[110:113]
	v_mfma_f32_16x16x32_bf16 v[106:109], v[142:145], v[182:185], v[106:109]
	v_mfma_f32_16x16x32_bf16 v[94:97], v[134:137], v[190:193], v[94:97]
	v_mfma_f32_16x16x32_bf16 v[90:93], v[142:145], v[190:193], v[90:93]
	v_mfma_f32_16x16x32_bf16 v[78:81], v[134:137], v[198:201], v[78:81]
	v_mfma_f32_16x16x32_bf16 v[74:77], v[142:145], v[198:201], v[74:77]
	s_setprio 0
	s_barrier
	s_add_i32 s20, s52, s40
	v_lshl_add_u64 v[222:223], s[34:35], 0, v[156:157]
	s_mov_b32 m0, s20
	ds_read_b128 v[202:205], v211
	ds_read_b128 v[206:209], v211 offset:1024
	ds_read_b128 v[214:217], v211 offset:2048
	ds_read_b128 v[218:221], v211 offset:3072
	global_load_lds_dwordx4 v[222:223], off
	v_lshl_add_u64 v[224:225], s[34:35], 0, v[160:161]
	s_add_i32 m0, s20, 0x2000
	s_nop 0
	global_load_lds_dwordx4 v[224:225], off
	s_barrier
	s_waitcnt lgkmcnt(0)
	s_setprio 1
	s_waitcnt lgkmcnt(0)
	v_mfma_f32_16x16x32_bf16 v[118:121], v[202:205], v[146:149], 0
	v_mfma_f32_16x16x32_bf16 v[114:117], v[214:217], v[146:149], 0
	v_mfma_f32_16x16x32_bf16 v[102:105], v[202:205], v[178:181], 0
	v_mfma_f32_16x16x32_bf16 v[98:101], v[214:217], v[178:181], 0
	v_mfma_f32_16x16x32_bf16 v[86:89], v[202:205], v[186:189], 0
	v_mfma_f32_16x16x32_bf16 v[82:85], v[214:217], v[186:189], 0
	v_mfma_f32_16x16x32_bf16 v[70:73], v[202:205], v[194:197], 0
	v_mfma_f32_16x16x32_bf16 v[66:69], v[214:217], v[194:197], 0
	v_mfma_f32_16x16x32_bf16 v[118:121], v[206:209], v[150:153], v[118:121]
	v_mfma_f32_16x16x32_bf16 v[114:117], v[218:221], v[150:153], v[114:117]
	v_mfma_f32_16x16x32_bf16 v[102:105], v[206:209], v[182:185], v[102:105]
	v_mfma_f32_16x16x32_bf16 v[98:101], v[218:221], v[182:185], v[98:101]
	v_mfma_f32_16x16x32_bf16 v[86:89], v[206:209], v[190:193], v[86:89]
	v_mfma_f32_16x16x32_bf16 v[82:85], v[218:221], v[190:193], v[82:85]
	v_mfma_f32_16x16x32_bf16 v[70:73], v[206:209], v[198:201], v[70:73]
	v_mfma_f32_16x16x32_bf16 v[66:69], v[218:221], v[198:201], v[66:69]
	s_setprio 0
	s_mov_b32 m0, s41
	v_lshl_add_u64 v[226:227], s[18:19], 0, v[154:155]
	s_barrier
	ds_read_b128 v[146:149], v210 offset:16384
	ds_read_b128 v[150:153], v210 offset:17408
	ds_read_b128 v[178:181], v210 offset:18432
	ds_read_b128 v[182:185], v210 offset:19456
	ds_read_b128 v[186:189], v210 offset:20480
	ds_read_b128 v[190:193], v210 offset:21504
	ds_read_b128 v[194:197], v210 offset:22528
	ds_read_b128 v[198:201], v210 offset:23552
	global_load_lds_dwordx4 v[226:227], off
	v_lshl_add_u64 v[228:229], s[18:19], 0, v[158:159]
	s_mov_b32 m0, s42
	s_nop 0
	global_load_lds_dwordx4 v[228:229], off
	s_barrier
	s_waitcnt lgkmcnt(0)
	s_setprio 1
	s_waitcnt lgkmcnt(0)
	v_mfma_f32_16x16x32_bf16 v[62:65], v[130:133], v[146:149], 0
	v_mfma_f32_16x16x32_bf16 v[58:61], v[138:141], v[146:149], 0
	v_mfma_f32_16x16x32_bf16 v[46:49], v[130:133], v[178:181], 0
	v_mfma_f32_16x16x32_bf16 v[42:45], v[138:141], v[178:181], 0
	v_mfma_f32_16x16x32_bf16 v[30:33], v[130:133], v[186:189], 0
	v_mfma_f32_16x16x32_bf16 v[26:29], v[138:141], v[186:189], 0
	v_mfma_f32_16x16x32_bf16 v[14:17], v[130:133], v[194:197], 0
	v_mfma_f32_16x16x32_bf16 v[10:13], v[138:141], v[194:197], 0
	v_mfma_f32_16x16x32_bf16 v[62:65], v[134:137], v[150:153], v[62:65]
	v_mfma_f32_16x16x32_bf16 v[58:61], v[142:145], v[150:153], v[58:61]
	v_mfma_f32_16x16x32_bf16 v[46:49], v[134:137], v[182:185], v[46:49]
	v_mfma_f32_16x16x32_bf16 v[42:45], v[142:145], v[182:185], v[42:45]
	v_mfma_f32_16x16x32_bf16 v[30:33], v[134:137], v[190:193], v[30:33]
	v_mfma_f32_16x16x32_bf16 v[26:29], v[142:145], v[190:193], v[26:29]
	v_mfma_f32_16x16x32_bf16 v[14:17], v[134:137], v[198:201], v[14:17]
	v_mfma_f32_16x16x32_bf16 v[10:13], v[142:145], v[198:201], v[10:13]
	s_setprio 0
	s_barrier
	s_add_u32 s20, s34, 0xb0000
	s_addc_u32 s21, s35, 0
	s_add_i32 s63, s53, s40
	v_lshl_add_u64 v[130:131], s[20:21], 0, v[156:157]
	s_mov_b32 m0, s63
	s_nop 0
	global_load_lds_dwordx4 v[130:131], off
	v_lshl_add_u64 v[130:131], s[20:21], 0, v[160:161]
	s_add_i32 m0, s63, 0x2000
	s_nop 0
	global_load_lds_dwordx4 v[130:131], off
	s_waitcnt vmcnt(6)
	s_barrier
	s_setprio 1
	v_mfma_f32_16x16x32_bf16 v[54:57], v[202:205], v[146:149], 0
	v_mfma_f32_16x16x32_bf16 v[50:53], v[214:217], v[146:149], 0
	v_mfma_f32_16x16x32_bf16 v[38:41], v[202:205], v[178:181], 0
	v_mfma_f32_16x16x32_bf16 v[34:37], v[214:217], v[178:181], 0
	v_mfma_f32_16x16x32_bf16 v[22:25], v[202:205], v[186:189], 0
	v_mfma_f32_16x16x32_bf16 v[18:21], v[214:217], v[186:189], 0
	v_mfma_f32_16x16x32_bf16 v[6:9], v[202:205], v[194:197], 0
	v_mfma_f32_16x16x32_bf16 v[2:5], v[214:217], v[194:197], 0
	v_mfma_f32_16x16x32_bf16 v[54:57], v[206:209], v[150:153], v[54:57]
	v_mfma_f32_16x16x32_bf16 v[50:53], v[218:221], v[150:153], v[50:53]
	v_mfma_f32_16x16x32_bf16 v[38:41], v[206:209], v[182:185], v[38:41]
	v_mfma_f32_16x16x32_bf16 v[34:37], v[218:221], v[182:185], v[34:37]
	v_mfma_f32_16x16x32_bf16 v[22:25], v[206:209], v[190:193], v[22:25]
	v_mfma_f32_16x16x32_bf16 v[18:21], v[218:221], v[190:193], v[18:21]
	v_mfma_f32_16x16x32_bf16 v[6:9], v[206:209], v[198:201], v[6:9]
	v_mfma_f32_16x16x32_bf16 v[2:5], v[218:221], v[198:201], v[2:5]
	s_setprio 0
	s_add_i32 s20, 0, 0x18000
	v_add_u32_e32 v142, s20, v165
	s_barrier
	ds_read_b128 v[130:133], v142
	ds_read_b128 v[134:137], v142 offset:1024
	ds_read_b128 v[138:141], v142 offset:2048
	ds_read_b128 v[142:145], v142 offset:3072
	s_add_u32 s18, s18, 0xb0000
	s_addc_u32 s19, s19, 0
	s_mov_b32 m0, s43
	v_lshl_add_u64 v[202:203], s[18:19], 0, v[154:155]
	ds_read_b128 v[146:149], v210 offset:32768
	ds_read_b128 v[150:153], v210 offset:33792
	ds_read_b128 v[178:181], v210 offset:34816
	ds_read_b128 v[182:185], v210 offset:35840
	ds_read_b128 v[186:189], v210 offset:36864
	ds_read_b128 v[190:193], v210 offset:37888
	ds_read_b128 v[194:197], v210 offset:38912
	ds_read_b128 v[198:201], v210 offset:39936
	global_load_lds_dwordx4 v[202:203], off
	v_lshl_add_u64 v[202:203], s[18:19], 0, v[158:159]
	s_mov_b32 m0, s44
	s_nop 0
	global_load_lds_dwordx4 v[202:203], off
	s_waitcnt lgkmcnt(8)
	s_barrier
	s_waitcnt lgkmcnt(0)
	s_setprio 1
	s_waitcnt lgkmcnt(0)
	v_mfma_f32_16x16x32_bf16 v[126:129], v[130:133], v[146:149], v[126:129]
	v_mfma_f32_16x16x32_bf16 v[122:125], v[138:141], v[146:149], v[122:125]
	v_mfma_f32_16x16x32_bf16 v[110:113], v[130:133], v[178:181], v[110:113]
	v_mfma_f32_16x16x32_bf16 v[106:109], v[138:141], v[178:181], v[106:109]
	v_mfma_f32_16x16x32_bf16 v[94:97], v[130:133], v[186:189], v[94:97]
	v_mfma_f32_16x16x32_bf16 v[90:93], v[138:141], v[186:189], v[90:93]
	v_mfma_f32_16x16x32_bf16 v[78:81], v[130:133], v[194:197], v[78:81]
	v_mfma_f32_16x16x32_bf16 v[74:77], v[138:141], v[194:197], v[74:77]
	v_mfma_f32_16x16x32_bf16 v[126:129], v[134:137], v[150:153], v[126:129]
	v_mfma_f32_16x16x32_bf16 v[122:125], v[142:145], v[150:153], v[122:125]
	v_mfma_f32_16x16x32_bf16 v[110:113], v[134:137], v[182:185], v[110:113]
	v_mfma_f32_16x16x32_bf16 v[106:109], v[142:145], v[182:185], v[106:109]
	v_mfma_f32_16x16x32_bf16 v[94:97], v[134:137], v[190:193], v[94:97]
	v_mfma_f32_16x16x32_bf16 v[90:93], v[142:145], v[190:193], v[90:93]
	v_mfma_f32_16x16x32_bf16 v[78:81], v[134:137], v[198:201], v[78:81]
	v_mfma_f32_16x16x32_bf16 v[74:77], v[142:145], v[198:201], v[74:77]
	s_setprio 0
	s_barrier
	s_add_i32 s21, 0, 0x1c000
	s_add_i32 s18, s20, s40
	v_add_u32_e32 v162, s21, v165
	v_lshl_add_u64 v[222:223], v[222:223], 0, s[14:15]
	s_mov_b32 m0, s18
	ds_read_b128 v[202:205], v162
	ds_read_b128 v[206:209], v162 offset:1024
	ds_read_b128 v[214:217], v162 offset:2048
	ds_read_b128 v[218:221], v162 offset:3072
	global_load_lds_dwordx4 v[222:223], off
	v_lshl_add_u64 v[222:223], v[224:225], 0, s[14:15]
	s_add_i32 m0, s18, 0x2000
	s_nop 0
	global_load_lds_dwordx4 v[222:223], off
	s_barrier
	s_waitcnt lgkmcnt(0)
	s_setprio 1
	s_waitcnt lgkmcnt(0)
	v_mfma_f32_16x16x32_bf16 v[118:121], v[202:205], v[146:149], v[118:121]
	v_mfma_f32_16x16x32_bf16 v[114:117], v[214:217], v[146:149], v[114:117]
	v_mfma_f32_16x16x32_bf16 v[102:105], v[202:205], v[178:181], v[102:105]
	v_mfma_f32_16x16x32_bf16 v[98:101], v[214:217], v[178:181], v[98:101]
	v_mfma_f32_16x16x32_bf16 v[86:89], v[202:205], v[186:189], v[86:89]
	v_mfma_f32_16x16x32_bf16 v[82:85], v[214:217], v[186:189], v[82:85]
	v_mfma_f32_16x16x32_bf16 v[70:73], v[202:205], v[194:197], v[70:73]
	v_mfma_f32_16x16x32_bf16 v[66:69], v[214:217], v[194:197], v[66:69]
	v_mfma_f32_16x16x32_bf16 v[118:121], v[206:209], v[150:153], v[118:121]
	v_mfma_f32_16x16x32_bf16 v[114:117], v[218:221], v[150:153], v[114:117]
	v_mfma_f32_16x16x32_bf16 v[102:105], v[206:209], v[182:185], v[102:105]
	v_mfma_f32_16x16x32_bf16 v[98:101], v[218:221], v[182:185], v[98:101]
	v_mfma_f32_16x16x32_bf16 v[86:89], v[206:209], v[190:193], v[86:89]
	v_mfma_f32_16x16x32_bf16 v[82:85], v[218:221], v[190:193], v[82:85]
	v_mfma_f32_16x16x32_bf16 v[70:73], v[206:209], v[198:201], v[70:73]
	v_mfma_f32_16x16x32_bf16 v[66:69], v[218:221], v[198:201], v[66:69]
	s_setprio 0
	s_mov_b32 m0, s48
	v_lshl_add_u64 v[222:223], v[226:227], 0, s[14:15]
	s_barrier
	ds_read_b128 v[146:149], v210 offset:49152
	ds_read_b128 v[150:153], v210 offset:50176
	ds_read_b128 v[178:181], v210 offset:51200
	ds_read_b128 v[182:185], v210 offset:52224
	ds_read_b128 v[186:189], v210 offset:53248
	ds_read_b128 v[190:193], v210 offset:54272
	ds_read_b128 v[194:197], v210 offset:55296
	ds_read_b128 v[198:201], v210 offset:56320
	global_load_lds_dwordx4 v[222:223], off
	v_lshl_add_u64 v[222:223], v[228:229], 0, s[14:15]
	s_mov_b32 m0, s49
	s_nop 0
	global_load_lds_dwordx4 v[222:223], off
	s_barrier
	s_waitcnt lgkmcnt(0)
	s_setprio 1
	s_waitcnt lgkmcnt(0)
	v_mfma_f32_16x16x32_bf16 v[62:65], v[130:133], v[146:149], v[62:65]
	v_mfma_f32_16x16x32_bf16 v[58:61], v[138:141], v[146:149], v[58:61]
	v_mfma_f32_16x16x32_bf16 v[46:49], v[130:133], v[178:181], v[46:49]
	v_mfma_f32_16x16x32_bf16 v[42:45], v[138:141], v[178:181], v[42:45]
	v_mfma_f32_16x16x32_bf16 v[30:33], v[130:133], v[186:189], v[30:33]
	v_mfma_f32_16x16x32_bf16 v[26:29], v[138:141], v[186:189], v[26:29]
	v_mfma_f32_16x16x32_bf16 v[14:17], v[130:133], v[194:197], v[14:17]
	v_mfma_f32_16x16x32_bf16 v[10:13], v[138:141], v[194:197], v[10:13]
	v_mfma_f32_16x16x32_bf16 v[62:65], v[134:137], v[150:153], v[62:65]
	v_mfma_f32_16x16x32_bf16 v[58:61], v[142:145], v[150:153], v[58:61]
	v_mfma_f32_16x16x32_bf16 v[46:49], v[134:137], v[182:185], v[46:49]
	v_mfma_f32_16x16x32_bf16 v[42:45], v[142:145], v[182:185], v[42:45]
	v_mfma_f32_16x16x32_bf16 v[30:33], v[134:137], v[190:193], v[30:33]
	v_mfma_f32_16x16x32_bf16 v[26:29], v[142:145], v[190:193], v[26:29]
	v_mfma_f32_16x16x32_bf16 v[14:17], v[134:137], v[198:201], v[14:17]
	v_mfma_f32_16x16x32_bf16 v[10:13], v[142:145], v[198:201], v[10:13]
	s_setprio 0
	s_barrier
	s_add_u32 s18, s34, 0xb0080
	s_addc_u32 s19, s35, 0
	s_add_i32 s20, s21, s40
	v_lshl_add_u64 v[130:131], s[18:19], 0, v[156:157]
	s_mov_b32 m0, s20
	s_nop 0
	global_load_lds_dwordx4 v[130:131], off
	v_lshl_add_u64 v[130:131], s[18:19], 0, v[160:161]
	s_add_i32 m0, s20, 0x2000
	s_nop 0
	global_load_lds_dwordx4 v[130:131], off
	s_waitcnt vmcnt(6)
	s_barrier
	s_setprio 1
	v_mfma_f32_16x16x32_bf16 v[54:57], v[202:205], v[146:149], v[54:57]
	v_mfma_f32_16x16x32_bf16 v[50:53], v[214:217], v[146:149], v[50:53]
	v_mfma_f32_16x16x32_bf16 v[38:41], v[202:205], v[178:181], v[38:41]
	v_mfma_f32_16x16x32_bf16 v[34:37], v[214:217], v[178:181], v[34:37]
	v_mfma_f32_16x16x32_bf16 v[22:25], v[202:205], v[186:189], v[22:25]
	v_mfma_f32_16x16x32_bf16 v[18:21], v[214:217], v[186:189], v[18:21]
	v_mfma_f32_16x16x32_bf16 v[6:9], v[202:205], v[194:197], v[6:9]
	v_mfma_f32_16x16x32_bf16 v[2:5], v[214:217], v[194:197], v[2:5]
	v_mfma_f32_16x16x32_bf16 v[54:57], v[206:209], v[150:153], v[54:57]
	v_mfma_f32_16x16x32_bf16 v[50:53], v[218:221], v[150:153], v[50:53]
	v_mfma_f32_16x16x32_bf16 v[38:41], v[206:209], v[182:185], v[38:41]
	v_mfma_f32_16x16x32_bf16 v[34:37], v[218:221], v[182:185], v[34:37]
	v_mfma_f32_16x16x32_bf16 v[22:25], v[206:209], v[190:193], v[22:25]
	v_mfma_f32_16x16x32_bf16 v[18:21], v[218:221], v[190:193], v[18:21]
	v_mfma_f32_16x16x32_bf16 v[6:9], v[206:209], v[198:201], v[6:9]
	v_mfma_f32_16x16x32_bf16 v[2:5], v[218:221], v[198:201], v[2:5]
	s_setprio 0
	s_add_i32 s62, s62, 2
	s_add_u32 s24, s24, 0x100
	s_addc_u32 s25, s25, 0
	s_add_u32 s60, s60, 0x100
	s_addc_u32 s61, s61, 0
	s_cmp_gt_u32 s62, 41
	s_barrier
